# v14: v12 + sample-attention keys interleaved across waves (key = 8j + wave)
# speedup vs baseline: 1.0027x; 1.0027x over previous
; #define LAS __attribute__((address_space(3)))
; DI void attn_sample_item(const Params& p, int item, ldsp lds, int tid_) {
;     ...
;   const int b = item >> 2, h = item & 3;
;   bf16_t* qx = (bf16_t*)(p.ws + B_QX);
;   const float* ck = p.in[6] + ((size_t)b * 256 * 4 + h) * 256;
;   const float* cv = p.in[7] + ((size_t)b * 256 * 4 + h) * 256;
;   LAS float* SC = (LAS float*)lds;
;   LAS float* PART = (LAS float*)(lds + 4096);
;   float q[4][4];
; #pragma unroll
;   for (int t = 0; t < 4; ++t) { f32x4 a = {0.f, 0.f, 0.f, 0.f}; const float* pp = (const float*)(p.ws + B_PART) + (size_t)(b * 4 + t) * 1024 + h * 256 + lane * 4;
; #pragma unroll
;     for (int kp = 0; kp < 4; ++kp) a += *(const f32x4*)(pp + (size_t)kp * 512 * 1024);
;     q[t][0] = a[0] * 0.0625f; q[t][1] = a[1] * 0.0625f; q[t][2] = a[2] * 0.0625f; q[t][3] = a[3] * 0.0625f; }
;   const bool b0 = lane & 1, b1 = lane & 2;
;   f32x4 kvA[16], kvB[16];
; #pragma unroll
;   for (int j = 0; j < 16; ++j) kvA[j] = __builtin_nontemporal_load((const f32x4*)(ck + (size_t)(wid * 32 + j) * 1024 + lane * 4));
; #pragma unroll
;   for (int j = 0; j < 16; ++j) kvB[j] = __builtin_nontemporal_load((const f32x4*)(ck + (size_t)(wid * 32 + 16 + j) * 1024 + lane * 4));
.LBB0_1604:
	s_ashr_i32 s4, s40, 2
	s_ashr_i32 s5, s4, 31
	s_lshl_b64 s[4:5], s[4:5], 18
	s_and_b32 s26, s0, 0x300
	v_mov_b32_e32 v222, v212
	s_or_b32 s4, s4, s26
	s_and_b32 s28, s40, -4
	s_lshl_b32 s6, s26, 2
	s_add_u32 s6, s36, s6
	v_and_b32_e32 v223, 63, v222
	s_addc_u32 s7, s37, 0
	v_lshlrev_b32_e32 v144, 4, v223
	s_lshl_b64 s[60:61], s[4:5], 2
	s_add_u32 s60, s12, s60
	s_addc_u32 s61, s13, s61
	v_ashrrev_i32_e32 v244, 6, v222
	v_lshlrev_b32_e32 v236, 5, v244
	s_ashr_i32 s29, s28, 31
	v_lshl_add_u64 v[48:49], s[6:7], 0, v[144:145]
	s_lshl_b64 s[6:7], s[28:29], 12
	v_lshl_add_u64 v[8:9], v[48:49], 0, s[6:7]
	v_add_co_u32_e32 v4, vcc, s3, v8
	s_or_b32 s6, s28, 1
	s_nop 0
	v_addc_co_u32_e32 v5, vcc, 0, v9, vcc
	v_add_co_u32_e32 v10, vcc, s33, v8
	s_ashr_i32 s7, s6, 31
	s_nop 0
	v_addc_co_u32_e32 v11, vcc, 0, v9, vcc
	v_add_co_u32_e32 v12, vcc, s38, v8
	s_lshl_b64 s[6:7], s[6:7], 12
	s_nop 0
	v_addc_co_u32_e32 v13, vcc, 0, v9, vcc
	v_lshl_add_u64 v[24:25], v[48:49], 0, s[6:7]
	v_add_co_u32_e32 v20, vcc, s3, v24
	s_or_b32 s6, s28, 2
	s_nop 0
	v_addc_co_u32_e32 v21, vcc, 0, v25, vcc
	v_add_co_u32_e32 v26, vcc, s33, v24
	s_ashr_i32 s7, s6, 31
	s_nop 0
	v_addc_co_u32_e32 v27, vcc, 0, v25, vcc
	v_add_co_u32_e32 v28, vcc, s38, v24
	s_lshl_b64 s[6:7], s[6:7], 12
	global_load_dwordx4 v[0:3], v[8:9], off
	s_nop 0
	global_load_dwordx4 v[4:7], v[4:5], off
	v_addc_co_u32_e32 v29, vcc, 0, v25, vcc
	v_lshl_add_u64 v[44:45], v[48:49], 0, s[6:7]
	global_load_dwordx4 v[8:11], v[10:11], off
	s_nop 0
	global_load_dwordx4 v[12:15], v[12:13], off
	s_nop 0
	global_load_dwordx4 v[16:19], v[24:25], off
	s_nop 0
	global_load_dwordx4 v[20:23], v[20:21], off
	v_add_co_u32_e32 v36, vcc, s3, v44
	global_load_dwordx4 v[24:27], v[26:27], off
	s_nop 0
	global_load_dwordx4 v[28:31], v[28:29], off
	v_addc_co_u32_e32 v37, vcc, 0, v45, vcc
	v_add_co_u32_e32 v40, vcc, s33, v44
	global_load_dwordx4 v[32:35], v[44:45], off
	s_nop 0
	global_load_dwordx4 v[36:39], v[36:37], off
	v_addc_co_u32_e32 v41, vcc, 0, v45, vcc
	v_add_co_u32_e32 v44, vcc, s38, v44
	global_load_dwordx4 v[40:43], v[40:41], off
	s_nop 0
	v_addc_co_u32_e32 v45, vcc, 0, v45, vcc
	global_load_dwordx4 v[44:47], v[44:45], off
	s_or_b32 s6, s40, 3
	s_ashr_i32 s7, s6, 31
	s_lshl_b64 s[6:7], s[6:7], 12
	s_lshl_b64 s[30:31], s[4:5], 2
	s_add_u32 s4, s12, s30
	s_addc_u32 s5, s13, s31
	s_waitcnt vmcnt(11)
	v_pk_add_f32 v[2:3], v[2:3], 0 op_sel_hi:[1,0]
	v_pk_add_f32 v[0:1], v[0:1], 0 op_sel_hi:[1,0]
	s_waitcnt vmcnt(10)
	v_pk_add_f32 v[2:3], v[2:3], v[6:7]
	v_pk_add_f32 v[0:1], v[0:1], v[4:5]
	s_waitcnt vmcnt(9)
	v_pk_add_f32 v[2:3], v[2:3], v[10:11]
	s_waitcnt vmcnt(7)
	v_pk_add_f32 v[4:5], v[18:19], 0 op_sel_hi:[1,0]
	v_pk_add_f32 v[6:7], v[16:17], 0 op_sel_hi:[1,0]
	v_pk_add_f32 v[0:1], v[0:1], v[8:9]
	s_waitcnt vmcnt(6)
	v_pk_add_f32 v[4:5], v[4:5], v[22:23]
	v_pk_add_f32 v[6:7], v[6:7], v[20:21]
	v_pk_add_f32 v[2:3], v[2:3], v[14:15]
	v_pk_add_f32 v[0:1], v[0:1], v[12:13]
	s_waitcnt vmcnt(5)
	v_pk_add_f32 v[4:5], v[4:5], v[26:27]
	v_pk_add_f32 v[6:7], v[6:7], v[24:25]
	v_mul_f32_e32 v228, 0x3d800000, v0
	v_mul_f32_e32 v231, 0x3d800000, v1
	v_mul_f32_e32 v229, 0x3d800000, v2
	v_mul_f32_e32 v225, 0x3d800000, v3
	s_waitcnt vmcnt(4)
	v_pk_add_f32 v[0:1], v[4:5], v[30:31]
	v_pk_add_f32 v[2:3], v[6:7], v[28:29]
	v_mul_f32_e32 v227, 0x3d800000, v0
	v_mul_f32_e32 v226, 0x3d800000, v2
	v_mul_f32_e32 v230, 0x3d800000, v3
	v_mul_f32_e32 v224, 0x3d800000, v1
	s_waitcnt vmcnt(3)
	v_pk_add_f32 v[0:1], v[34:35], 0 op_sel_hi:[1,0]
	v_pk_add_f32 v[2:3], v[32:33], 0 op_sel_hi:[1,0]
	s_waitcnt vmcnt(2)
	v_pk_add_f32 v[0:1], v[0:1], v[38:39]
	v_pk_add_f32 v[2:3], v[2:3], v[36:37]
	s_waitcnt vmcnt(1)
	v_pk_add_f32 v[0:1], v[0:1], v[42:43]
	v_pk_add_f32 v[2:3], v[2:3], v[40:41]
	s_waitcnt vmcnt(0)
	v_pk_add_f32 v[210:211], v[0:1], v[46:47]
	v_pk_add_f32 v[0:1], v[2:3], v[44:45]
	v_mul_f32_e32 v233, 0x3d800000, v210
	v_mul_f32_e32 v232, 0x3d800000, v0
	v_mul_f32_e32 v234, 0x3d800000, v1
	v_lshl_add_u64 v[0:1], v[48:49], 0, s[6:7]
	v_add_co_u32_e32 v2, vcc, s3, v0
	v_ashrrev_i32_e32 v210, 6, v222
	s_nop 0
	v_addc_co_u32_e32 v3, vcc, 0, v1, vcc
	global_load_dwordx4 v[128:131], v[0:1], off
	global_load_dwordx4 v[132:135], v[2:3], off
	v_add_co_u32_e32 v2, vcc, s33, v0
	v_mul_f32_e32 v211, 0x3d800000, v211
	s_nop 0
	v_addc_co_u32_e32 v3, vcc, 0, v1, vcc
	v_add_co_u32_e32 v0, vcc, s38, v0
	v_cmp_lt_i32_e64 s[6:7], v218, v216
	s_nop 0
	v_addc_co_u32_e32 v1, vcc, 0, v1, vcc
	global_load_dwordx4 v[136:139], v[2:3], off
	global_load_dwordx4 v[140:143], v[0:1], off
	v_add_u32_e32 v240, 0, v244
	v_lshlrev_b32_e32 v162, 12, v240
	v_mov_b32_e32 v163, 0
	v_add_u32_e32 v124, v162, v144
	global_load_dwordx4 v[124:127], v124, s[60:61] nt
	v_add_u32_e32 v240, 8, v244
	v_lshlrev_b32_e32 v166, 12, v240
	v_mov_b32_e32 v167, 0
	v_add_u32_e32 v120, v166, v144
	global_load_dwordx4 v[120:123], v120, s[60:61] nt
	v_add_u32_e32 v240, 16, v244
	v_lshlrev_b32_e32 v168, 12, v240
	v_mov_b32_e32 v169, 0
	v_add_u32_e32 v116, v168, v144
	global_load_dwordx4 v[116:119], v116, s[60:61] nt
	v_add_u32_e32 v240, 24, v244
	v_lshlrev_b32_e32 v172, 12, v240
	v_mov_b32_e32 v173, 0
	v_add_u32_e32 v112, v172, v144
	global_load_dwordx4 v[112:115], v112, s[60:61] nt
	v_add_u32_e32 v240, 32, v244
	v_lshlrev_b32_e32 v176, 12, v240
	v_mov_b32_e32 v177, 0
	v_add_u32_e32 v108, v176, v144
	global_load_dwordx4 v[108:111], v108, s[60:61] nt
	v_add_u32_e32 v240, 40, v244
	v_lshlrev_b32_e32 v180, 12, v240
	v_mov_b32_e32 v181, 0
	v_add_u32_e32 v104, v180, v144
	global_load_dwordx4 v[104:107], v104, s[60:61] nt
	v_add_u32_e32 v240, 48, v244
	v_lshlrev_b32_e32 v182, 12, v240
	v_mov_b32_e32 v183, 0
; DI void attn_sample_item(const Params& p, int item, ldsp lds, int tid_) {
;     ...
;   for (int j = 0; j < 16; ++j) kvA[j] = __builtin_nontemporal_load((const f32x4*)(ck + (size_t)(wid * 32 + j) * 1024 + lane * 4));
; #pragma unroll
;   for (int j = 0; j < 16; ++j) kvB[j] = __builtin_nontemporal_load((const f32x4*)(ck + (size_t)(wid * 32 + 16 + j) * 1024 + lane * 4));
	v_add_u32_e32 v100, v182, v144
	global_load_dwordx4 v[100:103], v100, s[60:61] nt
	v_add_u32_e32 v240, 56, v244
	v_lshlrev_b32_e32 v186, 12, v240
	v_mov_b32_e32 v187, 0
	v_add_u32_e32 v96, v186, v144
	global_load_dwordx4 v[96:99], v96, s[60:61] nt
	v_add_u32_e32 v240, 64, v244
	v_lshlrev_b32_e32 v190, 12, v240
	v_mov_b32_e32 v191, 0
	v_add_u32_e32 v92, v190, v144
	global_load_dwordx4 v[92:95], v92, s[60:61] nt
	v_add_u32_e32 v240, 72, v244
	v_lshlrev_b32_e32 v194, 12, v240
	v_mov_b32_e32 v195, 0
	v_add_u32_e32 v88, v194, v144
	global_load_dwordx4 v[88:91], v88, s[60:61] nt
	v_add_u32_e32 v240, 80, v244
	v_lshlrev_b32_e32 v198, 12, v240
	v_mov_b32_e32 v199, 0
	v_add_u32_e32 v84, v198, v144
	global_load_dwordx4 v[84:87], v84, s[60:61] nt
	v_add_u32_e32 v240, 88, v244
	v_lshlrev_b32_e32 v200, 12, v240
	v_mov_b32_e32 v201, 0
	v_add_u32_e32 v80, v200, v144
	global_load_dwordx4 v[80:83], v80, s[60:61] nt
	v_add_u32_e32 v240, 96, v244
	v_lshlrev_b32_e32 v202, 12, v240
	v_mov_b32_e32 v203, 0
	v_add_u32_e32 v76, v202, v144
	global_load_dwordx4 v[76:79], v76, s[60:61] nt
	v_add_u32_e32 v240, 104, v244
	v_lshlrev_b32_e32 v204, 12, v240
	v_mov_b32_e32 v205, 0
	v_add_u32_e32 v72, v204, v144
	global_load_dwordx4 v[72:75], v72, s[60:61] nt
	v_add_u32_e32 v240, 112, v244
	v_lshlrev_b32_e32 v206, 12, v240
	v_mov_b32_e32 v207, 0
	v_add_u32_e32 v68, v206, v144
	global_load_dwordx4 v[68:71], v68, s[60:61] nt
	v_add_u32_e32 v240, 120, v244
	v_lshlrev_b32_e32 v208, 12, v240
	v_mov_b32_e32 v209, 0
	v_add_u32_e32 v64, v208, v144
	global_load_dwordx4 v[64:67], v64, s[60:61] nt
	v_add_u32_e32 v240, 128, v244
	v_lshlrev_b32_e32 v146, 12, v240
	v_mov_b32_e32 v147, 0
	v_add_u32_e32 v60, v146, v144
	global_load_dwordx4 v[60:63], v60, s[60:61] nt
	v_add_u32_e32 v240, 136, v244
	v_lshlrev_b32_e32 v148, 12, v240
	v_mov_b32_e32 v149, 0
	v_add_u32_e32 v56, v148, v144
	global_load_dwordx4 v[56:59], v56, s[60:61] nt
	v_add_u32_e32 v240, 144, v244
	v_lshlrev_b32_e32 v150, 12, v240
	v_mov_b32_e32 v151, 0
	v_add_u32_e32 v52, v150, v144
	global_load_dwordx4 v[52:55], v52, s[60:61] nt
	v_add_u32_e32 v240, 152, v244
	v_lshlrev_b32_e32 v152, 12, v240
	v_mov_b32_e32 v153, 0
	v_add_u32_e32 v48, v152, v144
	global_load_dwordx4 v[48:51], v48, s[60:61] nt
	v_add_u32_e32 v240, 160, v244
	v_lshlrev_b32_e32 v154, 12, v240
	v_mov_b32_e32 v155, 0
	v_add_u32_e32 v44, v154, v144
	global_load_dwordx4 v[44:47], v44, s[60:61] nt
	v_add_u32_e32 v240, 168, v244
	v_lshlrev_b32_e32 v156, 12, v240
	v_mov_b32_e32 v157, 0
	v_add_u32_e32 v40, v156, v144
	global_load_dwordx4 v[40:43], v40, s[60:61] nt
	v_add_u32_e32 v240, 176, v244
	v_lshlrev_b32_e32 v158, 12, v240
	v_mov_b32_e32 v159, 0
	v_add_u32_e32 v36, v158, v144
	global_load_dwordx4 v[36:39], v36, s[60:61] nt
	v_add_u32_e32 v240, 184, v244
	v_lshlrev_b32_e32 v160, 12, v240
	v_mov_b32_e32 v161, 0
	v_add_u32_e32 v32, v160, v144
	global_load_dwordx4 v[32:35], v32, s[60:61] nt
	v_add_u32_e32 v240, 192, v244
	v_lshlrev_b32_e32 v164, 12, v240
	v_mov_b32_e32 v165, 0
	v_add_u32_e32 v28, v164, v144
	global_load_dwordx4 v[28:31], v28, s[60:61] nt
	v_add_u32_e32 v240, 200, v244
	v_lshlrev_b32_e32 v170, 12, v240
	v_mov_b32_e32 v171, 0
	v_add_u32_e32 v24, v170, v144
	global_load_dwordx4 v[24:27], v24, s[60:61] nt
	v_add_u32_e32 v240, 208, v244
	v_lshlrev_b32_e32 v174, 12, v240
	v_mov_b32_e32 v175, 0
	v_add_u32_e32 v20, v174, v144
	global_load_dwordx4 v[20:23], v20, s[60:61] nt
	v_add_u32_e32 v240, 216, v244
	v_lshlrev_b32_e32 v178, 12, v240
	v_mov_b32_e32 v179, 0
	v_add_u32_e32 v16, v178, v144
	global_load_dwordx4 v[16:19], v16, s[60:61] nt
	v_add_u32_e32 v240, 224, v244
	v_lshlrev_b32_e32 v184, 12, v240
	v_mov_b32_e32 v185, 0
	v_add_u32_e32 v12, v184, v144
	global_load_dwordx4 v[12:15], v12, s[60:61] nt
	v_add_u32_e32 v240, 232, v244
	v_lshlrev_b32_e32 v188, 12, v240
	v_mov_b32_e32 v189, 0
	v_add_u32_e32 v8, v188, v144
	global_load_dwordx4 v[8:11], v8, s[60:61] nt
	v_add_u32_e32 v240, 240, v244
	v_lshlrev_b32_e32 v192, 12, v240
	v_mov_b32_e32 v193, 0
	v_add_u32_e32 v4, v192, v144
	global_load_dwordx4 v[4:7], v4, s[60:61] nt
	v_add_u32_e32 v240, 248, v244
	v_lshlrev_b32_e32 v196, 12, v240
	v_mov_b32_e32 v197, 0
	v_add_u32_e32 v0, v196, v144
	global_load_dwordx4 v[0:3], v0, s[60:61] nt
	s_waitcnt vmcnt(35)
	v_pk_add_f32 v[128:129], v[128:129], 0 op_sel_hi:[1,0]
	v_pk_add_f32 v[130:131], v[130:131], 0 op_sel_hi:[1,0]
	s_waitcnt vmcnt(34)
	v_pk_add_f32 v[128:129], v[128:129], v[132:133]
	v_pk_add_f32 v[130:131], v[130:131], v[134:135]
	s_waitcnt vmcnt(33)
	v_pk_add_f32 v[128:129], v[128:129], v[136:137]
	v_pk_add_f32 v[130:131], v[130:131], v[138:139]
	s_waitcnt vmcnt(32)
	v_pk_add_f32 v[128:129], v[128:129], v[140:141]
	v_pk_add_f32 v[130:131], v[130:131], v[142:143]
	v_mul_f32_e32 v138, 0x3d800000, v129
	v_mul_f32_e32 v135, 0x3d800000, v128
	v_mul_f32_e32 v134, 0x3d800000, v131
	s_add_u32 s66, s14, s30
	s_addc_u32 s67, s15, s31
	v_mul_f32_e32 v137, 0x3d800000, v130
	v_lshlrev_b32_e32 v128, 2, v215
	v_lshlrev_b32_e32 v129, 2, v217
	v_lshlrev_b32_e32 v130, 2, v218
	v_lshlrev_b32_e32 v131, 2, v219
	v_lshlrev_b32_e32 v132, 2, v220
	v_lshlrev_b32_e32 v133, 2, v221
	v_lshl_add_u32 v136, v210, 7, 16
	v_and_b32_e32 v139, 3, v223
	v_bfrev_b32_e32 v139, v139
	v_lshrrev_b32_e32 v139, 20, v139
	v_and_b32_e32 v235, -4, v223
	v_add3_u32 v235, v136, v139, v235
	v_mov_b32_e32 v236, v228
	v_mov_b32_e32 v237, v226
	v_mov_b32_e32 v238, v231
	v_mov_b32_e32 v239, v230
	v_mov_b32_e32 v240, v229
	v_mov_b32_e32 v241, v227
	v_mov_b32_e32 v242, v225
	v_mov_b32_e32 v243, v224
	v_mov_b32_e32 v244, v232
	v_mov_b32_e32 v245, v135
	v_mov_b32_e32 v246, v234
	v_mov_b32_e32 v247, v138
	v_mov_b32_e32 v248, v233
	v_mov_b32_e32 v249, v137
	v_mov_b32_e32 v250, v211
	v_mov_b32_e32 v251, v134
	s_mov_b32 vcc_lo, 0x55555555
	s_mov_b32 vcc_hi, 0x55555555
	s_mov_b32 s4, 0x33333333
	s_mov_b32 s5, 0x33333333
	s_mov_b32 s6, 0x0f0f0f0f
	s_mov_b32 s7, 0x0f0f0f0f
	s_mov_b32 s64, 0x00ff00ff
	s_mov_b32 s65, 0x00ff00ff
	s_waitcnt vmcnt(31)
	v_pk_mul_f32 v[252:253], v[236:237], v[124:125] op_sel_hi:[1,0]
	v_pk_mul_f32 v[254:255], v[244:245], v[124:125] op_sel_hi:[1,0]
	v_pk_fma_f32 v[252:253], v[238:239], v[124:125], v[252:253] op_sel:[0,1,0]
	v_pk_fma_f32 v[254:255], v[246:247], v[124:125], v[254:255] op_sel:[0,1,0]
	v_pk_fma_f32 v[252:253], v[240:241], v[126:127], v[252:253] op_sel_hi:[1,0,1]
	v_pk_fma_f32 v[254:255], v[248:249], v[126:127], v[254:255] op_sel_hi:[1,0,1]
	v_pk_fma_f32 v[252:253], v[242:243], v[126:127], v[252:253] op_sel:[0,1,0]
	v_pk_fma_f32 v[254:255], v[250:251], v[126:127], v[254:255] op_sel:[0,1,0]
	s_waitcnt vmcnt(30)
	v_pk_mul_f32 v[140:141], v[236:237], v[120:121] op_sel_hi:[1,0]
	v_pk_mul_f32 v[142:143], v[244:245], v[120:121] op_sel_hi:[1,0]
	v_pk_fma_f32 v[140:141], v[238:239], v[120:121], v[140:141] op_sel:[0,1,0]
	v_pk_fma_f32 v[142:143], v[246:247], v[120:121], v[142:143] op_sel:[0,1,0]
	v_pk_fma_f32 v[140:141], v[240:241], v[122:123], v[140:141] op_sel_hi:[1,0,1]
	v_pk_fma_f32 v[142:143], v[248:249], v[122:123], v[142:143] op_sel_hi:[1,0,1]
	v_pk_fma_f32 v[140:141], v[242:243], v[122:123], v[140:141] op_sel:[0,1,0]
	v_pk_fma_f32 v[142:143], v[250:251], v[122:123], v[142:143] op_sel:[0,1,0]
	v_add_f32_dpp v124, v252, v252 quad_perm:[1,0,3,2] row_mask:0xf bank_mask:0xf
	v_add_f32_dpp v125, v253, v253 quad_perm:[1,0,3,2] row_mask:0xf bank_mask:0xf
	v_add_f32_dpp v126, v254, v254 quad_perm:[1,0,3,2] row_mask:0xf bank_mask:0xf
	v_add_f32_dpp v127, v255, v255 quad_perm:[1,0,3,2] row_mask:0xf bank_mask:0xf
	v_cndmask_b32_e32 v124, v126, v124, vcc
	v_cndmask_b32_e32 v125, v127, v125, vcc
	s_waitcnt vmcnt(29)
	v_pk_mul_f32 v[252:253], v[236:237], v[116:117] op_sel_hi:[1,0]
	v_pk_mul_f32 v[254:255], v[244:245], v[116:117] op_sel_hi:[1,0]
	v_pk_fma_f32 v[252:253], v[238:239], v[116:117], v[252:253] op_sel:[0,1,0]
	v_pk_fma_f32 v[254:255], v[246:247], v[116:117], v[254:255] op_sel:[0,1,0]
	v_pk_fma_f32 v[252:253], v[240:241], v[118:119], v[252:253] op_sel_hi:[1,0,1]
	v_pk_fma_f32 v[254:255], v[248:249], v[118:119], v[254:255] op_sel_hi:[1,0,1]
	v_pk_fma_f32 v[252:253], v[242:243], v[118:119], v[252:253] op_sel:[0,1,0]
	v_pk_fma_f32 v[254:255], v[250:251], v[118:119], v[254:255] op_sel:[0,1,0]
	v_add_f32_dpp v120, v140, v140 quad_perm:[1,0,3,2] row_mask:0xf bank_mask:0xf
	v_add_f32_dpp v121, v141, v141 quad_perm:[1,0,3,2] row_mask:0xf bank_mask:0xf
	v_add_f32_dpp v122, v142, v142 quad_perm:[1,0,3,2] row_mask:0xf bank_mask:0xf
	v_add_f32_dpp v123, v143, v143 quad_perm:[1,0,3,2] row_mask:0xf bank_mask:0xf
	v_cndmask_b32_e32 v120, v122, v120, vcc
	v_cndmask_b32_e32 v121, v123, v121, vcc
	v_add_f32_dpp v126, v124, v124 quad_perm:[2,3,0,1] row_mask:0xf bank_mask:0xf
	v_add_f32_dpp v127, v125, v125 quad_perm:[2,3,0,1] row_mask:0xf bank_mask:0xf
	v_cndmask_b32_e64 v124, v127, v126, s[4:5]
	s_waitcnt vmcnt(28)
	v_pk_mul_f32 v[140:141], v[236:237], v[112:113] op_sel_hi:[1,0]
	v_pk_mul_f32 v[142:143], v[244:245], v[112:113] op_sel_hi:[1,0]
	v_pk_fma_f32 v[140:141], v[238:239], v[112:113], v[140:141] op_sel:[0,1,0]
	v_pk_fma_f32 v[142:143], v[246:247], v[112:113], v[142:143] op_sel:[0,1,0]
	v_pk_fma_f32 v[140:141], v[240:241], v[114:115], v[140:141] op_sel_hi:[1,0,1]
	v_pk_fma_f32 v[142:143], v[248:249], v[114:115], v[142:143] op_sel_hi:[1,0,1]
	v_pk_fma_f32 v[140:141], v[242:243], v[114:115], v[140:141] op_sel:[0,1,0]
	v_pk_fma_f32 v[142:143], v[250:251], v[114:115], v[142:143] op_sel:[0,1,0]
	v_add_f32_dpp v116, v252, v252 quad_perm:[1,0,3,2] row_mask:0xf bank_mask:0xf
	v_add_f32_dpp v117, v253, v253 quad_perm:[1,0,3,2] row_mask:0xf bank_mask:0xf
	v_add_f32_dpp v118, v254, v254 quad_perm:[1,0,3,2] row_mask:0xf bank_mask:0xf
	v_add_f32_dpp v119, v255, v255 quad_perm:[1,0,3,2] row_mask:0xf bank_mask:0xf
	v_cndmask_b32_e32 v116, v118, v116, vcc
	v_cndmask_b32_e32 v117, v119, v117, vcc
	v_add_f32_dpp v122, v120, v120 quad_perm:[2,3,0,1] row_mask:0xf bank_mask:0xf
	v_add_f32_dpp v123, v121, v121 quad_perm:[2,3,0,1] row_mask:0xf bank_mask:0xf
	v_cndmask_b32_e64 v120, v123, v122, s[4:5]
	v_cndmask_b32_e64 v125, v120, v124, s[6:7]
	v_cndmask_b32_e64 v126, v124, v120, s[6:7]
	s_waitcnt vmcnt(27)
	v_pk_mul_f32 v[252:253], v[236:237], v[108:109] op_sel_hi:[1,0]
	v_pk_mul_f32 v[254:255], v[244:245], v[108:109] op_sel_hi:[1,0]
	v_pk_fma_f32 v[252:253], v[238:239], v[108:109], v[252:253] op_sel:[0,1,0]
	v_pk_fma_f32 v[254:255], v[246:247], v[108:109], v[254:255] op_sel:[0,1,0]
	v_pk_fma_f32 v[252:253], v[240:241], v[110:111], v[252:253] op_sel_hi:[1,0,1]
	v_pk_fma_f32 v[254:255], v[248:249], v[110:111], v[254:255] op_sel_hi:[1,0,1]
	v_pk_fma_f32 v[252:253], v[242:243], v[110:111], v[252:253] op_sel:[0,1,0]
	v_pk_fma_f32 v[254:255], v[250:251], v[110:111], v[254:255] op_sel:[0,1,0]
	v_add_f32_dpp v124, v126, v125 row_ror:4 row_mask:0xf bank_mask:0xf
	v_add_f32_dpp v112, v140, v140 quad_perm:[1,0,3,2] row_mask:0xf bank_mask:0xf
	v_add_f32_dpp v113, v141, v141 quad_perm:[1,0,3,2] row_mask:0xf bank_mask:0xf
	v_add_f32_dpp v114, v142, v142 quad_perm:[1,0,3,2] row_mask:0xf bank_mask:0xf
	v_add_f32_dpp v115, v143, v143 quad_perm:[1,0,3,2] row_mask:0xf bank_mask:0xf
	v_cndmask_b32_e32 v112, v114, v112, vcc
	v_cndmask_b32_e32 v113, v115, v113, vcc
	v_add_f32_dpp v118, v116, v116 quad_perm:[2,3,0,1] row_mask:0xf bank_mask:0xf
	v_add_f32_dpp v119, v117, v117 quad_perm:[2,3,0,1] row_mask:0xf bank_mask:0xf
	v_cndmask_b32_e64 v116, v119, v118, s[4:5]
	s_waitcnt vmcnt(26)
	v_pk_mul_f32 v[140:141], v[236:237], v[104:105] op_sel_hi:[1,0]
	v_pk_mul_f32 v[142:143], v[244:245], v[104:105] op_sel_hi:[1,0]
	v_pk_fma_f32 v[140:141], v[238:239], v[104:105], v[140:141] op_sel:[0,1,0]
	v_pk_fma_f32 v[142:143], v[246:247], v[104:105], v[142:143] op_sel:[0,1,0]
	v_pk_fma_f32 v[140:141], v[240:241], v[106:107], v[140:141] op_sel_hi:[1,0,1]
	v_pk_fma_f32 v[142:143], v[248:249], v[106:107], v[142:143] op_sel_hi:[1,0,1]
	v_pk_fma_f32 v[140:141], v[242:243], v[106:107], v[140:141] op_sel:[0,1,0]
	v_pk_fma_f32 v[142:143], v[250:251], v[106:107], v[142:143] op_sel:[0,1,0]
	v_add_f32_dpp v108, v252, v252 quad_perm:[1,0,3,2] row_mask:0xf bank_mask:0xf
	v_add_f32_dpp v109, v253, v253 quad_perm:[1,0,3,2] row_mask:0xf bank_mask:0xf
	v_add_f32_dpp v110, v254, v254 quad_perm:[1,0,3,2] row_mask:0xf bank_mask:0xf
	v_add_f32_dpp v111, v255, v255 quad_perm:[1,0,3,2] row_mask:0xf bank_mask:0xf
	v_cndmask_b32_e32 v108, v110, v108, vcc
	v_cndmask_b32_e32 v109, v111, v109, vcc
	v_add_f32_dpp v114, v112, v112 quad_perm:[2,3,0,1] row_mask:0xf bank_mask:0xf
	v_add_f32_dpp v115, v113, v113 quad_perm:[2,3,0,1] row_mask:0xf bank_mask:0xf
	v_cndmask_b32_e64 v112, v115, v114, s[4:5]
	v_cndmask_b32_e64 v117, v112, v116, s[6:7]
	v_cndmask_b32_e64 v118, v116, v112, s[6:7]
	s_waitcnt vmcnt(25)
	v_pk_mul_f32 v[252:253], v[236:237], v[100:101] op_sel_hi:[1,0]
	v_pk_mul_f32 v[254:255], v[244:245], v[100:101] op_sel_hi:[1,0]
	v_pk_fma_f32 v[252:253], v[238:239], v[100:101], v[252:253] op_sel:[0,1,0]
	v_pk_fma_f32 v[254:255], v[246:247], v[100:101], v[254:255] op_sel:[0,1,0]
	v_pk_fma_f32 v[252:253], v[240:241], v[102:103], v[252:253] op_sel_hi:[1,0,1]
	v_pk_fma_f32 v[254:255], v[248:249], v[102:103], v[254:255] op_sel_hi:[1,0,1]
	v_pk_fma_f32 v[252:253], v[242:243], v[102:103], v[252:253] op_sel:[0,1,0]
	v_pk_fma_f32 v[254:255], v[250:251], v[102:103], v[254:255] op_sel:[0,1,0]
	v_add_f32_dpp v116, v118, v117 row_ror:4 row_mask:0xf bank_mask:0xf
	v_cndmask_b32_e64 v125, v116, v124, s[64:65]
	v_cndmask_b32_e64 v126, v124, v116, s[64:65]
	v_add_f32_dpp v104, v140, v140 quad_perm:[1,0,3,2] row_mask:0xf bank_mask:0xf
	v_add_f32_dpp v105, v141, v141 quad_perm:[1,0,3,2] row_mask:0xf bank_mask:0xf
	v_add_f32_dpp v106, v142, v142 quad_perm:[1,0,3,2] row_mask:0xf bank_mask:0xf
	v_add_f32_dpp v107, v143, v143 quad_perm:[1,0,3,2] row_mask:0xf bank_mask:0xf
	v_cndmask_b32_e32 v104, v106, v104, vcc
	v_cndmask_b32_e32 v105, v107, v105, vcc
	v_add_f32_dpp v110, v108, v108 quad_perm:[2,3,0,1] row_mask:0xf bank_mask:0xf
	v_add_f32_dpp v111, v109, v109 quad_perm:[2,3,0,1] row_mask:0xf bank_mask:0xf
	v_cndmask_b32_e64 v108, v111, v110, s[4:5]
	s_waitcnt vmcnt(24)
	v_pk_mul_f32 v[140:141], v[236:237], v[96:97] op_sel_hi:[1,0]
	v_pk_mul_f32 v[142:143], v[244:245], v[96:97] op_sel_hi:[1,0]
	v_pk_fma_f32 v[140:141], v[238:239], v[96:97], v[140:141] op_sel:[0,1,0]
	v_pk_fma_f32 v[142:143], v[246:247], v[96:97], v[142:143] op_sel:[0,1,0]
	v_pk_fma_f32 v[140:141], v[240:241], v[98:99], v[140:141] op_sel_hi:[1,0,1]
	v_pk_fma_f32 v[142:143], v[248:249], v[98:99], v[142:143] op_sel_hi:[1,0,1]
	v_pk_fma_f32 v[140:141], v[242:243], v[98:99], v[140:141] op_sel:[0,1,0]
	v_pk_fma_f32 v[142:143], v[250:251], v[98:99], v[142:143] op_sel:[0,1,0]
	v_add_f32_dpp v124, v126, v125 row_ror:8 row_mask:0xf bank_mask:0xf
	v_add_f32_dpp v100, v252, v252 quad_perm:[1,0,3,2] row_mask:0xf bank_mask:0xf
	v_add_f32_dpp v101, v253, v253 quad_perm:[1,0,3,2] row_mask:0xf bank_mask:0xf
	v_add_f32_dpp v102, v254, v254 quad_perm:[1,0,3,2] row_mask:0xf bank_mask:0xf
	v_add_f32_dpp v103, v255, v255 quad_perm:[1,0,3,2] row_mask:0xf bank_mask:0xf
	v_cndmask_b32_e32 v100, v102, v100, vcc
	v_cndmask_b32_e32 v101, v103, v101, vcc
	v_add_f32_dpp v106, v104, v104 quad_perm:[2,3,0,1] row_mask:0xf bank_mask:0xf
	v_add_f32_dpp v107, v105, v105 quad_perm:[2,3,0,1] row_mask:0xf bank_mask:0xf
	v_cndmask_b32_e64 v104, v107, v106, s[4:5]
	v_cndmask_b32_e64 v109, v104, v108, s[6:7]
	v_cndmask_b32_e64 v110, v108, v104, s[6:7]
	s_waitcnt vmcnt(23)
	v_pk_mul_f32 v[252:253], v[236:237], v[92:93] op_sel_hi:[1,0]
	v_pk_mul_f32 v[254:255], v[244:245], v[92:93] op_sel_hi:[1,0]
	v_pk_fma_f32 v[252:253], v[238:239], v[92:93], v[252:253] op_sel:[0,1,0]
	v_pk_fma_f32 v[254:255], v[246:247], v[92:93], v[254:255] op_sel:[0,1,0]
	v_pk_fma_f32 v[252:253], v[240:241], v[94:95], v[252:253] op_sel_hi:[1,0,1]
	v_pk_fma_f32 v[254:255], v[248:249], v[94:95], v[254:255] op_sel_hi:[1,0,1]
	v_pk_fma_f32 v[252:253], v[242:243], v[94:95], v[252:253] op_sel:[0,1,0]
	v_pk_fma_f32 v[254:255], v[250:251], v[94:95], v[254:255] op_sel:[0,1,0]
	v_add_f32_dpp v108, v110, v109 row_ror:4 row_mask:0xf bank_mask:0xf
	v_add_f32_dpp v96, v140, v140 quad_perm:[1,0,3,2] row_mask:0xf bank_mask:0xf
	v_add_f32_dpp v97, v141, v141 quad_perm:[1,0,3,2] row_mask:0xf bank_mask:0xf
	v_add_f32_dpp v98, v142, v142 quad_perm:[1,0,3,2] row_mask:0xf bank_mask:0xf
	v_add_f32_dpp v99, v143, v143 quad_perm:[1,0,3,2] row_mask:0xf bank_mask:0xf
	v_cndmask_b32_e32 v96, v98, v96, vcc
	v_cndmask_b32_e32 v97, v99, v97, vcc
	v_add_f32_dpp v102, v100, v100 quad_perm:[2,3,0,1] row_mask:0xf bank_mask:0xf
	v_add_f32_dpp v103, v101, v101 quad_perm:[2,3,0,1] row_mask:0xf bank_mask:0xf
	v_cndmask_b32_e64 v100, v103, v102, s[4:5]
	s_waitcnt vmcnt(22)
	v_pk_mul_f32 v[140:141], v[236:237], v[88:89] op_sel_hi:[1,0]
	v_pk_mul_f32 v[142:143], v[244:245], v[88:89] op_sel_hi:[1,0]
	v_pk_fma_f32 v[140:141], v[238:239], v[88:89], v[140:141] op_sel:[0,1,0]
	v_pk_fma_f32 v[142:143], v[246:247], v[88:89], v[142:143] op_sel:[0,1,0]
	v_pk_fma_f32 v[140:141], v[240:241], v[90:91], v[140:141] op_sel_hi:[1,0,1]
	v_pk_fma_f32 v[142:143], v[248:249], v[90:91], v[142:143] op_sel_hi:[1,0,1]
	v_pk_fma_f32 v[140:141], v[242:243], v[90:91], v[140:141] op_sel:[0,1,0]
	v_pk_fma_f32 v[142:143], v[250:251], v[90:91], v[142:143] op_sel:[0,1,0]
	v_add_f32_dpp v92, v252, v252 quad_perm:[1,0,3,2] row_mask:0xf bank_mask:0xf
	v_add_f32_dpp v93, v253, v253 quad_perm:[1,0,3,2] row_mask:0xf bank_mask:0xf
	v_add_f32_dpp v94, v254, v254 quad_perm:[1,0,3,2] row_mask:0xf bank_mask:0xf
	v_add_f32_dpp v95, v255, v255 quad_perm:[1,0,3,2] row_mask:0xf bank_mask:0xf
	v_cndmask_b32_e32 v92, v94, v92, vcc
	v_cndmask_b32_e32 v93, v95, v93, vcc
	v_add_f32_dpp v98, v96, v96 quad_perm:[2,3,0,1] row_mask:0xf bank_mask:0xf
	v_add_f32_dpp v99, v97, v97 quad_perm:[2,3,0,1] row_mask:0xf bank_mask:0xf
	v_cndmask_b32_e64 v96, v99, v98, s[4:5]
	v_cndmask_b32_e64 v101, v96, v100, s[6:7]
	v_cndmask_b32_e64 v102, v100, v96, s[6:7]
	s_waitcnt vmcnt(21)
	v_pk_mul_f32 v[252:253], v[236:237], v[84:85] op_sel_hi:[1,0]
	v_pk_mul_f32 v[254:255], v[244:245], v[84:85] op_sel_hi:[1,0]
	v_pk_fma_f32 v[252:253], v[238:239], v[84:85], v[252:253] op_sel:[0,1,0]
	v_pk_fma_f32 v[254:255], v[246:247], v[84:85], v[254:255] op_sel:[0,1,0]
	v_pk_fma_f32 v[252:253], v[240:241], v[86:87], v[252:253] op_sel_hi:[1,0,1]
	v_pk_fma_f32 v[254:255], v[248:249], v[86:87], v[254:255] op_sel_hi:[1,0,1]
	v_pk_fma_f32 v[252:253], v[242:243], v[86:87], v[252:253] op_sel:[0,1,0]
	v_pk_fma_f32 v[254:255], v[250:251], v[86:87], v[254:255] op_sel:[0,1,0]
	v_add_f32_dpp v100, v102, v101 row_ror:4 row_mask:0xf bank_mask:0xf
	v_cndmask_b32_e64 v109, v100, v108, s[64:65]
	v_cndmask_b32_e64 v110, v108, v100, s[64:65]
	v_add_f32_dpp v88, v140, v140 quad_perm:[1,0,3,2] row_mask:0xf bank_mask:0xf
	v_add_f32_dpp v89, v141, v141 quad_perm:[1,0,3,2] row_mask:0xf bank_mask:0xf
	v_add_f32_dpp v90, v142, v142 quad_perm:[1,0,3,2] row_mask:0xf bank_mask:0xf
	v_add_f32_dpp v91, v143, v143 quad_perm:[1,0,3,2] row_mask:0xf bank_mask:0xf
	v_cndmask_b32_e32 v88, v90, v88, vcc
	v_cndmask_b32_e32 v89, v91, v89, vcc
	v_add_f32_dpp v94, v92, v92 quad_perm:[2,3,0,1] row_mask:0xf bank_mask:0xf
	v_add_f32_dpp v95, v93, v93 quad_perm:[2,3,0,1] row_mask:0xf bank_mask:0xf
	v_cndmask_b32_e64 v92, v95, v94, s[4:5]
	s_waitcnt vmcnt(20)
	v_pk_mul_f32 v[140:141], v[236:237], v[80:81] op_sel_hi:[1,0]
	v_pk_mul_f32 v[142:143], v[244:245], v[80:81] op_sel_hi:[1,0]
	v_pk_fma_f32 v[140:141], v[238:239], v[80:81], v[140:141] op_sel:[0,1,0]
	v_pk_fma_f32 v[142:143], v[246:247], v[80:81], v[142:143] op_sel:[0,1,0]
	v_pk_fma_f32 v[140:141], v[240:241], v[82:83], v[140:141] op_sel_hi:[1,0,1]
	v_pk_fma_f32 v[142:143], v[248:249], v[82:83], v[142:143] op_sel_hi:[1,0,1]
	v_pk_fma_f32 v[140:141], v[242:243], v[82:83], v[140:141] op_sel:[0,1,0]
	v_pk_fma_f32 v[142:143], v[250:251], v[82:83], v[142:143] op_sel:[0,1,0]
	v_add_f32_dpp v108, v110, v109 row_ror:8 row_mask:0xf bank_mask:0xf
	v_add_f32_dpp v84, v252, v252 quad_perm:[1,0,3,2] row_mask:0xf bank_mask:0xf
	v_add_f32_dpp v85, v253, v253 quad_perm:[1,0,3,2] row_mask:0xf bank_mask:0xf
	v_add_f32_dpp v86, v254, v254 quad_perm:[1,0,3,2] row_mask:0xf bank_mask:0xf
	v_add_f32_dpp v87, v255, v255 quad_perm:[1,0,3,2] row_mask:0xf bank_mask:0xf
	v_cndmask_b32_e32 v84, v86, v84, vcc
	v_cndmask_b32_e32 v85, v87, v85, vcc
	v_add_f32_dpp v90, v88, v88 quad_perm:[2,3,0,1] row_mask:0xf bank_mask:0xf
	v_add_f32_dpp v91, v89, v89 quad_perm:[2,3,0,1] row_mask:0xf bank_mask:0xf
	v_cndmask_b32_e64 v88, v91, v90, s[4:5]
	v_cndmask_b32_e64 v93, v88, v92, s[6:7]
	v_cndmask_b32_e64 v94, v92, v88, s[6:7]
	s_waitcnt vmcnt(19)
	v_pk_mul_f32 v[252:253], v[236:237], v[76:77] op_sel_hi:[1,0]
	v_pk_mul_f32 v[254:255], v[244:245], v[76:77] op_sel_hi:[1,0]
	v_pk_fma_f32 v[252:253], v[238:239], v[76:77], v[252:253] op_sel:[0,1,0]
	v_pk_fma_f32 v[254:255], v[246:247], v[76:77], v[254:255] op_sel:[0,1,0]
	v_pk_fma_f32 v[252:253], v[240:241], v[78:79], v[252:253] op_sel_hi:[1,0,1]
	v_pk_fma_f32 v[254:255], v[248:249], v[78:79], v[254:255] op_sel_hi:[1,0,1]
	v_pk_fma_f32 v[252:253], v[242:243], v[78:79], v[252:253] op_sel:[0,1,0]
	v_pk_fma_f32 v[254:255], v[250:251], v[78:79], v[254:255] op_sel:[0,1,0]
	v_permlane16_swap_b32_e32 v124, v108
	v_add_f32_e32 v124, v124, v108
	v_add_f32_dpp v92, v94, v93 row_ror:4 row_mask:0xf bank_mask:0xf
	v_add_f32_dpp v80, v140, v140 quad_perm:[1,0,3,2] row_mask:0xf bank_mask:0xf
	v_add_f32_dpp v81, v141, v141 quad_perm:[1,0,3,2] row_mask:0xf bank_mask:0xf
	v_add_f32_dpp v82, v142, v142 quad_perm:[1,0,3,2] row_mask:0xf bank_mask:0xf
	v_add_f32_dpp v83, v143, v143 quad_perm:[1,0,3,2] row_mask:0xf bank_mask:0xf
	v_cndmask_b32_e32 v80, v82, v80, vcc
	v_cndmask_b32_e32 v81, v83, v81, vcc
	v_add_f32_dpp v86, v84, v84 quad_perm:[2,3,0,1] row_mask:0xf bank_mask:0xf
	v_add_f32_dpp v87, v85, v85 quad_perm:[2,3,0,1] row_mask:0xf bank_mask:0xf
	v_cndmask_b32_e64 v84, v87, v86, s[4:5]
	s_waitcnt vmcnt(18)
	v_pk_mul_f32 v[140:141], v[236:237], v[72:73] op_sel_hi:[1,0]
	v_pk_mul_f32 v[142:143], v[244:245], v[72:73] op_sel_hi:[1,0]
	v_pk_fma_f32 v[140:141], v[238:239], v[72:73], v[140:141] op_sel:[0,1,0]
	v_pk_fma_f32 v[142:143], v[246:247], v[72:73], v[142:143] op_sel:[0,1,0]
	v_pk_fma_f32 v[140:141], v[240:241], v[74:75], v[140:141] op_sel_hi:[1,0,1]
	v_pk_fma_f32 v[142:143], v[248:249], v[74:75], v[142:143] op_sel_hi:[1,0,1]
	v_pk_fma_f32 v[140:141], v[242:243], v[74:75], v[140:141] op_sel:[0,1,0]
	v_pk_fma_f32 v[142:143], v[250:251], v[74:75], v[142:143] op_sel:[0,1,0]
	v_add_f32_dpp v76, v252, v252 quad_perm:[1,0,3,2] row_mask:0xf bank_mask:0xf
	v_add_f32_dpp v77, v253, v253 quad_perm:[1,0,3,2] row_mask:0xf bank_mask:0xf
	v_add_f32_dpp v78, v254, v254 quad_perm:[1,0,3,2] row_mask:0xf bank_mask:0xf
	v_add_f32_dpp v79, v255, v255 quad_perm:[1,0,3,2] row_mask:0xf bank_mask:0xf
	v_cndmask_b32_e32 v76, v78, v76, vcc
	v_cndmask_b32_e32 v77, v79, v77, vcc
	v_add_f32_dpp v82, v80, v80 quad_perm:[2,3,0,1] row_mask:0xf bank_mask:0xf
	v_add_f32_dpp v83, v81, v81 quad_perm:[2,3,0,1] row_mask:0xf bank_mask:0xf
	v_cndmask_b32_e64 v80, v83, v82, s[4:5]
	v_cndmask_b32_e64 v85, v80, v84, s[6:7]
	v_cndmask_b32_e64 v86, v84, v80, s[6:7]
	s_waitcnt vmcnt(17)
	v_pk_mul_f32 v[252:253], v[236:237], v[68:69] op_sel_hi:[1,0]
	v_pk_mul_f32 v[254:255], v[244:245], v[68:69] op_sel_hi:[1,0]
	v_pk_fma_f32 v[252:253], v[238:239], v[68:69], v[252:253] op_sel:[0,1,0]
	v_pk_fma_f32 v[254:255], v[246:247], v[68:69], v[254:255] op_sel:[0,1,0]
	v_pk_fma_f32 v[252:253], v[240:241], v[70:71], v[252:253] op_sel_hi:[1,0,1]
	v_pk_fma_f32 v[254:255], v[248:249], v[70:71], v[254:255] op_sel_hi:[1,0,1]
	v_pk_fma_f32 v[252:253], v[242:243], v[70:71], v[252:253] op_sel:[0,1,0]
	v_pk_fma_f32 v[254:255], v[250:251], v[70:71], v[254:255] op_sel:[0,1,0]
	v_add_f32_dpp v84, v86, v85 row_ror:4 row_mask:0xf bank_mask:0xf
	v_cndmask_b32_e64 v93, v84, v92, s[64:65]
	v_cndmask_b32_e64 v94, v92, v84, s[64:65]
	v_add_f32_dpp v72, v140, v140 quad_perm:[1,0,3,2] row_mask:0xf bank_mask:0xf
	v_add_f32_dpp v73, v141, v141 quad_perm:[1,0,3,2] row_mask:0xf bank_mask:0xf
	v_add_f32_dpp v74, v142, v142 quad_perm:[1,0,3,2] row_mask:0xf bank_mask:0xf
	v_add_f32_dpp v75, v143, v143 quad_perm:[1,0,3,2] row_mask:0xf bank_mask:0xf
	v_cndmask_b32_e32 v72, v74, v72, vcc
	v_cndmask_b32_e32 v73, v75, v73, vcc
	v_add_f32_dpp v78, v76, v76 quad_perm:[2,3,0,1] row_mask:0xf bank_mask:0xf
	v_add_f32_dpp v79, v77, v77 quad_perm:[2,3,0,1] row_mask:0xf bank_mask:0xf
	v_cndmask_b32_e64 v76, v79, v78, s[4:5]
	s_waitcnt vmcnt(16)
	v_pk_mul_f32 v[140:141], v[236:237], v[64:65] op_sel_hi:[1,0]
	v_pk_mul_f32 v[142:143], v[244:245], v[64:65] op_sel_hi:[1,0]
	v_pk_fma_f32 v[140:141], v[238:239], v[64:65], v[140:141] op_sel:[0,1,0]
	v_pk_fma_f32 v[142:143], v[246:247], v[64:65], v[142:143] op_sel:[0,1,0]
	v_pk_fma_f32 v[140:141], v[240:241], v[66:67], v[140:141] op_sel_hi:[1,0,1]
	v_pk_fma_f32 v[142:143], v[248:249], v[66:67], v[142:143] op_sel_hi:[1,0,1]
	v_pk_fma_f32 v[140:141], v[242:243], v[66:67], v[140:141] op_sel:[0,1,0]
	v_pk_fma_f32 v[142:143], v[250:251], v[66:67], v[142:143] op_sel:[0,1,0]
	v_add_f32_dpp v92, v94, v93 row_ror:8 row_mask:0xf bank_mask:0xf
	v_add_f32_dpp v68, v252, v252 quad_perm:[1,0,3,2] row_mask:0xf bank_mask:0xf
	v_add_f32_dpp v69, v253, v253 quad_perm:[1,0,3,2] row_mask:0xf bank_mask:0xf
	v_add_f32_dpp v70, v254, v254 quad_perm:[1,0,3,2] row_mask:0xf bank_mask:0xf
	v_add_f32_dpp v71, v255, v255 quad_perm:[1,0,3,2] row_mask:0xf bank_mask:0xf
	v_cndmask_b32_e32 v68, v70, v68, vcc
	v_cndmask_b32_e32 v69, v71, v69, vcc
	v_add_f32_dpp v74, v72, v72 quad_perm:[2,3,0,1] row_mask:0xf bank_mask:0xf
	v_add_f32_dpp v75, v73, v73 quad_perm:[2,3,0,1] row_mask:0xf bank_mask:0xf
	v_cndmask_b32_e64 v72, v75, v74, s[4:5]
	v_cndmask_b32_e64 v77, v72, v76, s[6:7]
	v_cndmask_b32_e64 v78, v76, v72, s[6:7]
	s_waitcnt vmcnt(15)
	v_pk_mul_f32 v[252:253], v[236:237], v[60:61] op_sel_hi:[1,0]
	v_pk_mul_f32 v[254:255], v[244:245], v[60:61] op_sel_hi:[1,0]
	v_pk_fma_f32 v[252:253], v[238:239], v[60:61], v[252:253] op_sel:[0,1,0]
	v_pk_fma_f32 v[254:255], v[246:247], v[60:61], v[254:255] op_sel:[0,1,0]
	v_pk_fma_f32 v[252:253], v[240:241], v[62:63], v[252:253] op_sel_hi:[1,0,1]
	v_pk_fma_f32 v[254:255], v[248:249], v[62:63], v[254:255] op_sel_hi:[1,0,1]
	v_pk_fma_f32 v[252:253], v[242:243], v[62:63], v[252:253] op_sel:[0,1,0]
	v_pk_fma_f32 v[254:255], v[250:251], v[62:63], v[254:255] op_sel:[0,1,0]
	v_add_f32_dpp v76, v78, v77 row_ror:4 row_mask:0xf bank_mask:0xf
	v_add_f32_dpp v64, v140, v140 quad_perm:[1,0,3,2] row_mask:0xf bank_mask:0xf
	v_add_f32_dpp v65, v141, v141 quad_perm:[1,0,3,2] row_mask:0xf bank_mask:0xf
	v_add_f32_dpp v66, v142, v142 quad_perm:[1,0,3,2] row_mask:0xf bank_mask:0xf
	v_add_f32_dpp v67, v143, v143 quad_perm:[1,0,3,2] row_mask:0xf bank_mask:0xf
	v_cndmask_b32_e32 v64, v66, v64, vcc
	v_cndmask_b32_e32 v65, v67, v65, vcc
	v_add_f32_dpp v70, v68, v68 quad_perm:[2,3,0,1] row_mask:0xf bank_mask:0xf
	v_add_f32_dpp v71, v69, v69 quad_perm:[2,3,0,1] row_mask:0xf bank_mask:0xf
	v_cndmask_b32_e64 v68, v71, v70, s[4:5]
	s_waitcnt vmcnt(14)
	v_pk_mul_f32 v[140:141], v[236:237], v[56:57] op_sel_hi:[1,0]
	v_pk_mul_f32 v[142:143], v[244:245], v[56:57] op_sel_hi:[1,0]
	v_pk_fma_f32 v[140:141], v[238:239], v[56:57], v[140:141] op_sel:[0,1,0]
	v_pk_fma_f32 v[142:143], v[246:247], v[56:57], v[142:143] op_sel:[0,1,0]
	v_pk_fma_f32 v[140:141], v[240:241], v[58:59], v[140:141] op_sel_hi:[1,0,1]
	v_pk_fma_f32 v[142:143], v[248:249], v[58:59], v[142:143] op_sel_hi:[1,0,1]
	v_pk_fma_f32 v[140:141], v[242:243], v[58:59], v[140:141] op_sel:[0,1,0]
	v_pk_fma_f32 v[142:143], v[250:251], v[58:59], v[142:143] op_sel:[0,1,0]
	v_add_f32_dpp v60, v252, v252 quad_perm:[1,0,3,2] row_mask:0xf bank_mask:0xf
	v_add_f32_dpp v61, v253, v253 quad_perm:[1,0,3,2] row_mask:0xf bank_mask:0xf
	v_add_f32_dpp v62, v254, v254 quad_perm:[1,0,3,2] row_mask:0xf bank_mask:0xf
	v_add_f32_dpp v63, v255, v255 quad_perm:[1,0,3,2] row_mask:0xf bank_mask:0xf
	v_cndmask_b32_e32 v60, v62, v60, vcc
	v_cndmask_b32_e32 v61, v63, v61, vcc
	v_add_f32_dpp v66, v64, v64 quad_perm:[2,3,0,1] row_mask:0xf bank_mask:0xf
	v_add_f32_dpp v67, v65, v65 quad_perm:[2,3,0,1] row_mask:0xf bank_mask:0xf
	v_cndmask_b32_e64 v64, v67, v66, s[4:5]
	v_cndmask_b32_e64 v69, v64, v68, s[6:7]
	v_cndmask_b32_e64 v70, v68, v64, s[6:7]
	s_waitcnt vmcnt(13)
	v_pk_mul_f32 v[252:253], v[236:237], v[52:53] op_sel_hi:[1,0]
	v_pk_mul_f32 v[254:255], v[244:245], v[52:53] op_sel_hi:[1,0]
	v_pk_fma_f32 v[252:253], v[238:239], v[52:53], v[252:253] op_sel:[0,1,0]
	v_pk_fma_f32 v[254:255], v[246:247], v[52:53], v[254:255] op_sel:[0,1,0]
	v_pk_fma_f32 v[252:253], v[240:241], v[54:55], v[252:253] op_sel_hi:[1,0,1]
	v_pk_fma_f32 v[254:255], v[248:249], v[54:55], v[254:255] op_sel_hi:[1,0,1]
	v_pk_fma_f32 v[252:253], v[242:243], v[54:55], v[252:253] op_sel:[0,1,0]
	v_pk_fma_f32 v[254:255], v[250:251], v[54:55], v[254:255] op_sel:[0,1,0]
	v_add_f32_dpp v68, v70, v69 row_ror:4 row_mask:0xf bank_mask:0xf
	v_cndmask_b32_e64 v77, v68, v76, s[64:65]
	v_cndmask_b32_e64 v78, v76, v68, s[64:65]
	v_add_f32_dpp v56, v140, v140 quad_perm:[1,0,3,2] row_mask:0xf bank_mask:0xf
	v_add_f32_dpp v57, v141, v141 quad_perm:[1,0,3,2] row_mask:0xf bank_mask:0xf
	v_add_f32_dpp v58, v142, v142 quad_perm:[1,0,3,2] row_mask:0xf bank_mask:0xf
	v_add_f32_dpp v59, v143, v143 quad_perm:[1,0,3,2] row_mask:0xf bank_mask:0xf
	v_cndmask_b32_e32 v56, v58, v56, vcc
	v_cndmask_b32_e32 v57, v59, v57, vcc
	v_add_f32_dpp v62, v60, v60 quad_perm:[2,3,0,1] row_mask:0xf bank_mask:0xf
	v_add_f32_dpp v63, v61, v61 quad_perm:[2,3,0,1] row_mask:0xf bank_mask:0xf
	v_cndmask_b32_e64 v60, v63, v62, s[4:5]
	s_waitcnt vmcnt(12)
	v_pk_mul_f32 v[140:141], v[236:237], v[48:49] op_sel_hi:[1,0]
	v_pk_mul_f32 v[142:143], v[244:245], v[48:49] op_sel_hi:[1,0]
	v_pk_fma_f32 v[140:141], v[238:239], v[48:49], v[140:141] op_sel:[0,1,0]
	v_pk_fma_f32 v[142:143], v[246:247], v[48:49], v[142:143] op_sel:[0,1,0]
	v_pk_fma_f32 v[140:141], v[240:241], v[50:51], v[140:141] op_sel_hi:[1,0,1]
	v_pk_fma_f32 v[142:143], v[248:249], v[50:51], v[142:143] op_sel_hi:[1,0,1]
	v_pk_fma_f32 v[140:141], v[242:243], v[50:51], v[140:141] op_sel:[0,1,0]
	v_pk_fma_f32 v[142:143], v[250:251], v[50:51], v[142:143] op_sel:[0,1,0]
	v_add_f32_dpp v76, v78, v77 row_ror:8 row_mask:0xf bank_mask:0xf
	v_add_f32_dpp v52, v252, v252 quad_perm:[1,0,3,2] row_mask:0xf bank_mask:0xf
	v_add_f32_dpp v53, v253, v253 quad_perm:[1,0,3,2] row_mask:0xf bank_mask:0xf
	v_add_f32_dpp v54, v254, v254 quad_perm:[1,0,3,2] row_mask:0xf bank_mask:0xf
	v_add_f32_dpp v55, v255, v255 quad_perm:[1,0,3,2] row_mask:0xf bank_mask:0xf
	v_cndmask_b32_e32 v52, v54, v52, vcc
	v_cndmask_b32_e32 v53, v55, v53, vcc
	v_add_f32_dpp v58, v56, v56 quad_perm:[2,3,0,1] row_mask:0xf bank_mask:0xf
	v_add_f32_dpp v59, v57, v57 quad_perm:[2,3,0,1] row_mask:0xf bank_mask:0xf
	v_cndmask_b32_e64 v56, v59, v58, s[4:5]
	v_cndmask_b32_e64 v61, v56, v60, s[6:7]
	v_cndmask_b32_e64 v62, v60, v56, s[6:7]
	s_waitcnt vmcnt(11)
	v_pk_mul_f32 v[252:253], v[236:237], v[44:45] op_sel_hi:[1,0]
	v_pk_mul_f32 v[254:255], v[244:245], v[44:45] op_sel_hi:[1,0]
	v_pk_fma_f32 v[252:253], v[238:239], v[44:45], v[252:253] op_sel:[0,1,0]
	v_pk_fma_f32 v[254:255], v[246:247], v[44:45], v[254:255] op_sel:[0,1,0]
	v_pk_fma_f32 v[252:253], v[240:241], v[46:47], v[252:253] op_sel_hi:[1,0,1]
	v_pk_fma_f32 v[254:255], v[248:249], v[46:47], v[254:255] op_sel_hi:[1,0,1]
	v_pk_fma_f32 v[252:253], v[242:243], v[46:47], v[252:253] op_sel:[0,1,0]
	v_pk_fma_f32 v[254:255], v[250:251], v[46:47], v[254:255] op_sel:[0,1,0]
	v_permlane16_swap_b32_e32 v92, v76
	v_add_f32_e32 v92, v92, v76
	v_add_f32_dpp v60, v62, v61 row_ror:4 row_mask:0xf bank_mask:0xf
	v_add_f32_dpp v48, v140, v140 quad_perm:[1,0,3,2] row_mask:0xf bank_mask:0xf
	v_add_f32_dpp v49, v141, v141 quad_perm:[1,0,3,2] row_mask:0xf bank_mask:0xf
	v_add_f32_dpp v50, v142, v142 quad_perm:[1,0,3,2] row_mask:0xf bank_mask:0xf
	v_add_f32_dpp v51, v143, v143 quad_perm:[1,0,3,2] row_mask:0xf bank_mask:0xf
	v_cndmask_b32_e32 v48, v50, v48, vcc
	v_cndmask_b32_e32 v49, v51, v49, vcc
	v_add_f32_dpp v54, v52, v52 quad_perm:[2,3,0,1] row_mask:0xf bank_mask:0xf
	v_add_f32_dpp v55, v53, v53 quad_perm:[2,3,0,1] row_mask:0xf bank_mask:0xf
	v_cndmask_b32_e64 v52, v55, v54, s[4:5]
	s_waitcnt vmcnt(10)
; DI void attn_sample_item(const Params& p, int item, ldsp lds, int tid_) {
;     ...
;   SC_SCORE(kvA, 0)
;   SC_SCORE(kvB, 1)
	v_pk_mul_f32 v[140:141], v[236:237], v[40:41] op_sel_hi:[1,0]
	v_pk_mul_f32 v[142:143], v[244:245], v[40:41] op_sel_hi:[1,0]
	v_pk_fma_f32 v[140:141], v[238:239], v[40:41], v[140:141] op_sel:[0,1,0]
	v_pk_fma_f32 v[142:143], v[246:247], v[40:41], v[142:143] op_sel:[0,1,0]
	v_pk_fma_f32 v[140:141], v[240:241], v[42:43], v[140:141] op_sel_hi:[1,0,1]
	v_pk_fma_f32 v[142:143], v[248:249], v[42:43], v[142:143] op_sel_hi:[1,0,1]
	v_pk_fma_f32 v[140:141], v[242:243], v[42:43], v[140:141] op_sel:[0,1,0]
	v_pk_fma_f32 v[142:143], v[250:251], v[42:43], v[142:143] op_sel:[0,1,0]
	v_permlane32_swap_b32_e32 v124, v92
	v_add_f32_e32 v124, v124, v92
	ds_write_b32 v235, v124
	v_add_f32_dpp v44, v252, v252 quad_perm:[1,0,3,2] row_mask:0xf bank_mask:0xf
	v_add_f32_dpp v45, v253, v253 quad_perm:[1,0,3,2] row_mask:0xf bank_mask:0xf
	v_add_f32_dpp v46, v254, v254 quad_perm:[1,0,3,2] row_mask:0xf bank_mask:0xf
	v_add_f32_dpp v47, v255, v255 quad_perm:[1,0,3,2] row_mask:0xf bank_mask:0xf
	v_cndmask_b32_e32 v44, v46, v44, vcc
	v_cndmask_b32_e32 v45, v47, v45, vcc
	v_add_f32_dpp v50, v48, v48 quad_perm:[2,3,0,1] row_mask:0xf bank_mask:0xf
	v_add_f32_dpp v51, v49, v49 quad_perm:[2,3,0,1] row_mask:0xf bank_mask:0xf
	v_cndmask_b32_e64 v48, v51, v50, s[4:5]
	v_cndmask_b32_e64 v53, v48, v52, s[6:7]
	v_cndmask_b32_e64 v54, v52, v48, s[6:7]
	s_waitcnt vmcnt(9)
	v_pk_mul_f32 v[252:253], v[236:237], v[36:37] op_sel_hi:[1,0]
	v_pk_mul_f32 v[254:255], v[244:245], v[36:37] op_sel_hi:[1,0]
	v_pk_fma_f32 v[252:253], v[238:239], v[36:37], v[252:253] op_sel:[0,1,0]
	v_pk_fma_f32 v[254:255], v[246:247], v[36:37], v[254:255] op_sel:[0,1,0]
	v_pk_fma_f32 v[252:253], v[240:241], v[38:39], v[252:253] op_sel_hi:[1,0,1]
	v_pk_fma_f32 v[254:255], v[248:249], v[38:39], v[254:255] op_sel_hi:[1,0,1]
	v_pk_fma_f32 v[252:253], v[242:243], v[38:39], v[252:253] op_sel:[0,1,0]
	v_pk_fma_f32 v[254:255], v[250:251], v[38:39], v[254:255] op_sel:[0,1,0]
	v_add_f32_dpp v52, v54, v53 row_ror:4 row_mask:0xf bank_mask:0xf
	v_cndmask_b32_e64 v61, v52, v60, s[64:65]
	v_cndmask_b32_e64 v62, v60, v52, s[64:65]
	v_add_f32_dpp v40, v140, v140 quad_perm:[1,0,3,2] row_mask:0xf bank_mask:0xf
	v_add_f32_dpp v41, v141, v141 quad_perm:[1,0,3,2] row_mask:0xf bank_mask:0xf
	v_add_f32_dpp v42, v142, v142 quad_perm:[1,0,3,2] row_mask:0xf bank_mask:0xf
	v_add_f32_dpp v43, v143, v143 quad_perm:[1,0,3,2] row_mask:0xf bank_mask:0xf
	v_cndmask_b32_e32 v40, v42, v40, vcc
	v_cndmask_b32_e32 v41, v43, v41, vcc
	v_add_f32_dpp v46, v44, v44 quad_perm:[2,3,0,1] row_mask:0xf bank_mask:0xf
	v_add_f32_dpp v47, v45, v45 quad_perm:[2,3,0,1] row_mask:0xf bank_mask:0xf
	v_cndmask_b32_e64 v44, v47, v46, s[4:5]
	s_waitcnt vmcnt(8)
	v_pk_mul_f32 v[140:141], v[236:237], v[32:33] op_sel_hi:[1,0]
	v_pk_mul_f32 v[142:143], v[244:245], v[32:33] op_sel_hi:[1,0]
	v_pk_fma_f32 v[140:141], v[238:239], v[32:33], v[140:141] op_sel:[0,1,0]
	v_pk_fma_f32 v[142:143], v[246:247], v[32:33], v[142:143] op_sel:[0,1,0]
	v_pk_fma_f32 v[140:141], v[240:241], v[34:35], v[140:141] op_sel_hi:[1,0,1]
	v_pk_fma_f32 v[142:143], v[248:249], v[34:35], v[142:143] op_sel_hi:[1,0,1]
	v_pk_fma_f32 v[140:141], v[242:243], v[34:35], v[140:141] op_sel:[0,1,0]
	v_pk_fma_f32 v[142:143], v[250:251], v[34:35], v[142:143] op_sel:[0,1,0]
	v_add_f32_dpp v60, v62, v61 row_ror:8 row_mask:0xf bank_mask:0xf
	v_add_f32_dpp v36, v252, v252 quad_perm:[1,0,3,2] row_mask:0xf bank_mask:0xf
	v_add_f32_dpp v37, v253, v253 quad_perm:[1,0,3,2] row_mask:0xf bank_mask:0xf
	v_add_f32_dpp v38, v254, v254 quad_perm:[1,0,3,2] row_mask:0xf bank_mask:0xf
	v_add_f32_dpp v39, v255, v255 quad_perm:[1,0,3,2] row_mask:0xf bank_mask:0xf
	v_cndmask_b32_e32 v36, v38, v36, vcc
	v_cndmask_b32_e32 v37, v39, v37, vcc
	v_add_f32_dpp v42, v40, v40 quad_perm:[2,3,0,1] row_mask:0xf bank_mask:0xf
	v_add_f32_dpp v43, v41, v41 quad_perm:[2,3,0,1] row_mask:0xf bank_mask:0xf
	v_cndmask_b32_e64 v40, v43, v42, s[4:5]
	v_cndmask_b32_e64 v45, v40, v44, s[6:7]
	v_cndmask_b32_e64 v46, v44, v40, s[6:7]
	s_waitcnt vmcnt(7)
	v_pk_mul_f32 v[252:253], v[236:237], v[28:29] op_sel_hi:[1,0]
	v_pk_mul_f32 v[254:255], v[244:245], v[28:29] op_sel_hi:[1,0]
	v_pk_fma_f32 v[252:253], v[238:239], v[28:29], v[252:253] op_sel:[0,1,0]
	v_pk_fma_f32 v[254:255], v[246:247], v[28:29], v[254:255] op_sel:[0,1,0]
	v_pk_fma_f32 v[252:253], v[240:241], v[30:31], v[252:253] op_sel_hi:[1,0,1]
	v_pk_fma_f32 v[254:255], v[248:249], v[30:31], v[254:255] op_sel_hi:[1,0,1]
	v_pk_fma_f32 v[252:253], v[242:243], v[30:31], v[252:253] op_sel:[0,1,0]
	v_pk_fma_f32 v[254:255], v[250:251], v[30:31], v[254:255] op_sel:[0,1,0]
	v_add_f32_dpp v44, v46, v45 row_ror:4 row_mask:0xf bank_mask:0xf
	v_add_f32_dpp v32, v140, v140 quad_perm:[1,0,3,2] row_mask:0xf bank_mask:0xf
	v_add_f32_dpp v33, v141, v141 quad_perm:[1,0,3,2] row_mask:0xf bank_mask:0xf
	v_add_f32_dpp v34, v142, v142 quad_perm:[1,0,3,2] row_mask:0xf bank_mask:0xf
	v_add_f32_dpp v35, v143, v143 quad_perm:[1,0,3,2] row_mask:0xf bank_mask:0xf
	v_cndmask_b32_e32 v32, v34, v32, vcc
	v_cndmask_b32_e32 v33, v35, v33, vcc
	v_add_f32_dpp v38, v36, v36 quad_perm:[2,3,0,1] row_mask:0xf bank_mask:0xf
	v_add_f32_dpp v39, v37, v37 quad_perm:[2,3,0,1] row_mask:0xf bank_mask:0xf
	v_cndmask_b32_e64 v36, v39, v38, s[4:5]
	s_waitcnt vmcnt(6)
	v_pk_mul_f32 v[140:141], v[236:237], v[24:25] op_sel_hi:[1,0]
	v_pk_mul_f32 v[142:143], v[244:245], v[24:25] op_sel_hi:[1,0]
	v_pk_fma_f32 v[140:141], v[238:239], v[24:25], v[140:141] op_sel:[0,1,0]
	v_pk_fma_f32 v[142:143], v[246:247], v[24:25], v[142:143] op_sel:[0,1,0]
	v_pk_fma_f32 v[140:141], v[240:241], v[26:27], v[140:141] op_sel_hi:[1,0,1]
	v_pk_fma_f32 v[142:143], v[248:249], v[26:27], v[142:143] op_sel_hi:[1,0,1]
	v_pk_fma_f32 v[140:141], v[242:243], v[26:27], v[140:141] op_sel:[0,1,0]
	v_pk_fma_f32 v[142:143], v[250:251], v[26:27], v[142:143] op_sel:[0,1,0]
	v_add_f32_dpp v28, v252, v252 quad_perm:[1,0,3,2] row_mask:0xf bank_mask:0xf
	v_add_f32_dpp v29, v253, v253 quad_perm:[1,0,3,2] row_mask:0xf bank_mask:0xf
	v_add_f32_dpp v30, v254, v254 quad_perm:[1,0,3,2] row_mask:0xf bank_mask:0xf
	v_add_f32_dpp v31, v255, v255 quad_perm:[1,0,3,2] row_mask:0xf bank_mask:0xf
	v_cndmask_b32_e32 v28, v30, v28, vcc
	v_cndmask_b32_e32 v29, v31, v29, vcc
	v_add_f32_dpp v34, v32, v32 quad_perm:[2,3,0,1] row_mask:0xf bank_mask:0xf
	v_add_f32_dpp v35, v33, v33 quad_perm:[2,3,0,1] row_mask:0xf bank_mask:0xf
	v_cndmask_b32_e64 v32, v35, v34, s[4:5]
	v_cndmask_b32_e64 v37, v32, v36, s[6:7]
	v_cndmask_b32_e64 v38, v36, v32, s[6:7]
	s_waitcnt vmcnt(5)
	v_pk_mul_f32 v[252:253], v[236:237], v[20:21] op_sel_hi:[1,0]
	v_pk_mul_f32 v[254:255], v[244:245], v[20:21] op_sel_hi:[1,0]
	v_pk_fma_f32 v[252:253], v[238:239], v[20:21], v[252:253] op_sel:[0,1,0]
	v_pk_fma_f32 v[254:255], v[246:247], v[20:21], v[254:255] op_sel:[0,1,0]
	v_pk_fma_f32 v[252:253], v[240:241], v[22:23], v[252:253] op_sel_hi:[1,0,1]
	v_pk_fma_f32 v[254:255], v[248:249], v[22:23], v[254:255] op_sel_hi:[1,0,1]
	v_pk_fma_f32 v[252:253], v[242:243], v[22:23], v[252:253] op_sel:[0,1,0]
	v_pk_fma_f32 v[254:255], v[250:251], v[22:23], v[254:255] op_sel:[0,1,0]
	v_add_f32_dpp v36, v38, v37 row_ror:4 row_mask:0xf bank_mask:0xf
	v_cndmask_b32_e64 v45, v36, v44, s[64:65]
	v_cndmask_b32_e64 v46, v44, v36, s[64:65]
	v_add_f32_dpp v24, v140, v140 quad_perm:[1,0,3,2] row_mask:0xf bank_mask:0xf
	v_add_f32_dpp v25, v141, v141 quad_perm:[1,0,3,2] row_mask:0xf bank_mask:0xf
	v_add_f32_dpp v26, v142, v142 quad_perm:[1,0,3,2] row_mask:0xf bank_mask:0xf
	v_add_f32_dpp v27, v143, v143 quad_perm:[1,0,3,2] row_mask:0xf bank_mask:0xf
	v_cndmask_b32_e32 v24, v26, v24, vcc
	v_cndmask_b32_e32 v25, v27, v25, vcc
	v_add_f32_dpp v30, v28, v28 quad_perm:[2,3,0,1] row_mask:0xf bank_mask:0xf
	v_add_f32_dpp v31, v29, v29 quad_perm:[2,3,0,1] row_mask:0xf bank_mask:0xf
	v_cndmask_b32_e64 v28, v31, v30, s[4:5]
	s_waitcnt vmcnt(4)
	v_pk_mul_f32 v[140:141], v[236:237], v[16:17] op_sel_hi:[1,0]
	v_pk_mul_f32 v[142:143], v[244:245], v[16:17] op_sel_hi:[1,0]
	v_pk_fma_f32 v[140:141], v[238:239], v[16:17], v[140:141] op_sel:[0,1,0]
	v_pk_fma_f32 v[142:143], v[246:247], v[16:17], v[142:143] op_sel:[0,1,0]
	v_pk_fma_f32 v[140:141], v[240:241], v[18:19], v[140:141] op_sel_hi:[1,0,1]
	v_pk_fma_f32 v[142:143], v[248:249], v[18:19], v[142:143] op_sel_hi:[1,0,1]
	v_pk_fma_f32 v[140:141], v[242:243], v[18:19], v[140:141] op_sel:[0,1,0]
	v_pk_fma_f32 v[142:143], v[250:251], v[18:19], v[142:143] op_sel:[0,1,0]
	v_add_f32_dpp v44, v46, v45 row_ror:8 row_mask:0xf bank_mask:0xf
	v_add_f32_dpp v20, v252, v252 quad_perm:[1,0,3,2] row_mask:0xf bank_mask:0xf
	v_add_f32_dpp v21, v253, v253 quad_perm:[1,0,3,2] row_mask:0xf bank_mask:0xf
	v_add_f32_dpp v22, v254, v254 quad_perm:[1,0,3,2] row_mask:0xf bank_mask:0xf
	v_add_f32_dpp v23, v255, v255 quad_perm:[1,0,3,2] row_mask:0xf bank_mask:0xf
	v_cndmask_b32_e32 v20, v22, v20, vcc
	v_cndmask_b32_e32 v21, v23, v21, vcc
	v_add_f32_dpp v26, v24, v24 quad_perm:[2,3,0,1] row_mask:0xf bank_mask:0xf
	v_add_f32_dpp v27, v25, v25 quad_perm:[2,3,0,1] row_mask:0xf bank_mask:0xf
	v_cndmask_b32_e64 v24, v27, v26, s[4:5]
	v_cndmask_b32_e64 v29, v24, v28, s[6:7]
	v_cndmask_b32_e64 v30, v28, v24, s[6:7]
	s_waitcnt vmcnt(3)
	v_pk_mul_f32 v[252:253], v[236:237], v[12:13] op_sel_hi:[1,0]
	v_pk_mul_f32 v[254:255], v[244:245], v[12:13] op_sel_hi:[1,0]
	v_pk_fma_f32 v[252:253], v[238:239], v[12:13], v[252:253] op_sel:[0,1,0]
	v_pk_fma_f32 v[254:255], v[246:247], v[12:13], v[254:255] op_sel:[0,1,0]
	v_pk_fma_f32 v[252:253], v[240:241], v[14:15], v[252:253] op_sel_hi:[1,0,1]
	v_pk_fma_f32 v[254:255], v[248:249], v[14:15], v[254:255] op_sel_hi:[1,0,1]
	v_pk_fma_f32 v[252:253], v[242:243], v[14:15], v[252:253] op_sel:[0,1,0]
	v_pk_fma_f32 v[254:255], v[250:251], v[14:15], v[254:255] op_sel:[0,1,0]
	v_permlane16_swap_b32_e32 v60, v44
	v_add_f32_e32 v60, v60, v44
	v_add_f32_dpp v28, v30, v29 row_ror:4 row_mask:0xf bank_mask:0xf
	v_add_f32_dpp v16, v140, v140 quad_perm:[1,0,3,2] row_mask:0xf bank_mask:0xf
	v_add_f32_dpp v17, v141, v141 quad_perm:[1,0,3,2] row_mask:0xf bank_mask:0xf
	v_add_f32_dpp v18, v142, v142 quad_perm:[1,0,3,2] row_mask:0xf bank_mask:0xf
	v_add_f32_dpp v19, v143, v143 quad_perm:[1,0,3,2] row_mask:0xf bank_mask:0xf
	v_cndmask_b32_e32 v16, v18, v16, vcc
	v_cndmask_b32_e32 v17, v19, v17, vcc
	v_add_f32_dpp v22, v20, v20 quad_perm:[2,3,0,1] row_mask:0xf bank_mask:0xf
	v_add_f32_dpp v23, v21, v21 quad_perm:[2,3,0,1] row_mask:0xf bank_mask:0xf
	v_cndmask_b32_e64 v20, v23, v22, s[4:5]
	s_waitcnt vmcnt(2)
	v_pk_mul_f32 v[140:141], v[236:237], v[8:9] op_sel_hi:[1,0]
	v_pk_mul_f32 v[142:143], v[244:245], v[8:9] op_sel_hi:[1,0]
	v_pk_fma_f32 v[140:141], v[238:239], v[8:9], v[140:141] op_sel:[0,1,0]
	v_pk_fma_f32 v[142:143], v[246:247], v[8:9], v[142:143] op_sel:[0,1,0]
	v_pk_fma_f32 v[140:141], v[240:241], v[10:11], v[140:141] op_sel_hi:[1,0,1]
	v_pk_fma_f32 v[142:143], v[248:249], v[10:11], v[142:143] op_sel_hi:[1,0,1]
	v_pk_fma_f32 v[140:141], v[242:243], v[10:11], v[140:141] op_sel:[0,1,0]
	v_pk_fma_f32 v[142:143], v[250:251], v[10:11], v[142:143] op_sel:[0,1,0]
	v_add_f32_dpp v12, v252, v252 quad_perm:[1,0,3,2] row_mask:0xf bank_mask:0xf
	v_add_f32_dpp v13, v253, v253 quad_perm:[1,0,3,2] row_mask:0xf bank_mask:0xf
	v_add_f32_dpp v14, v254, v254 quad_perm:[1,0,3,2] row_mask:0xf bank_mask:0xf
	v_add_f32_dpp v15, v255, v255 quad_perm:[1,0,3,2] row_mask:0xf bank_mask:0xf
	v_cndmask_b32_e32 v12, v14, v12, vcc
	v_cndmask_b32_e32 v13, v15, v13, vcc
	v_add_f32_dpp v18, v16, v16 quad_perm:[2,3,0,1] row_mask:0xf bank_mask:0xf
	v_add_f32_dpp v19, v17, v17 quad_perm:[2,3,0,1] row_mask:0xf bank_mask:0xf
	v_cndmask_b32_e64 v16, v19, v18, s[4:5]
	v_cndmask_b32_e64 v21, v16, v20, s[6:7]
	v_cndmask_b32_e64 v22, v20, v16, s[6:7]
	s_waitcnt vmcnt(1)
	v_pk_mul_f32 v[252:253], v[236:237], v[4:5] op_sel_hi:[1,0]
	v_pk_mul_f32 v[254:255], v[244:245], v[4:5] op_sel_hi:[1,0]
	v_pk_fma_f32 v[252:253], v[238:239], v[4:5], v[252:253] op_sel:[0,1,0]
	v_pk_fma_f32 v[254:255], v[246:247], v[4:5], v[254:255] op_sel:[0,1,0]
	v_pk_fma_f32 v[252:253], v[240:241], v[6:7], v[252:253] op_sel_hi:[1,0,1]
	v_pk_fma_f32 v[254:255], v[248:249], v[6:7], v[254:255] op_sel_hi:[1,0,1]
	v_pk_fma_f32 v[252:253], v[242:243], v[6:7], v[252:253] op_sel:[0,1,0]
	v_pk_fma_f32 v[254:255], v[250:251], v[6:7], v[254:255] op_sel:[0,1,0]
	v_add_f32_dpp v20, v22, v21 row_ror:4 row_mask:0xf bank_mask:0xf
	v_cndmask_b32_e64 v29, v20, v28, s[64:65]
	v_cndmask_b32_e64 v30, v28, v20, s[64:65]
	v_add_f32_dpp v8, v140, v140 quad_perm:[1,0,3,2] row_mask:0xf bank_mask:0xf
	v_add_f32_dpp v9, v141, v141 quad_perm:[1,0,3,2] row_mask:0xf bank_mask:0xf
	v_add_f32_dpp v10, v142, v142 quad_perm:[1,0,3,2] row_mask:0xf bank_mask:0xf
	v_add_f32_dpp v11, v143, v143 quad_perm:[1,0,3,2] row_mask:0xf bank_mask:0xf
	v_cndmask_b32_e32 v8, v10, v8, vcc
	v_cndmask_b32_e32 v9, v11, v9, vcc
	v_add_f32_dpp v14, v12, v12 quad_perm:[2,3,0,1] row_mask:0xf bank_mask:0xf
	v_add_f32_dpp v15, v13, v13 quad_perm:[2,3,0,1] row_mask:0xf bank_mask:0xf
	v_cndmask_b32_e64 v12, v15, v14, s[4:5]
	s_waitcnt vmcnt(0)
; DI void lbar() { asm volatile("s_waitcnt lgkmcnt(0)" ::: "memory"); __builtin_amdgcn_s_barrier(); asm volatile("" ::: "memory"); }
; DI void attn_sample_item(const Params& p, int item, ldsp lds, int tid_) {
;     ...
;   SC_SCORE(kvA, 0)
;   SC_SCORE(kvB, 1)
;     ...
;   f32x4 vvA[16], vvB[16];
; #pragma unroll
;   for (int j = 0; j < 16; ++j) vvA[j] = __builtin_nontemporal_load((const f32x4*)(cv + (size_t)(wid * 32 + j) * 1024 + lane * 4));
;   lbar();
	v_pk_mul_f32 v[140:141], v[236:237], v[0:1] op_sel_hi:[1,0]
	v_pk_mul_f32 v[142:143], v[244:245], v[0:1] op_sel_hi:[1,0]
	v_pk_fma_f32 v[140:141], v[238:239], v[0:1], v[140:141] op_sel:[0,1,0]
	v_pk_fma_f32 v[142:143], v[246:247], v[0:1], v[142:143] op_sel:[0,1,0]
	v_pk_fma_f32 v[140:141], v[240:241], v[2:3], v[140:141] op_sel_hi:[1,0,1]
	v_pk_fma_f32 v[142:143], v[248:249], v[2:3], v[142:143] op_sel_hi:[1,0,1]
	v_pk_fma_f32 v[140:141], v[242:243], v[2:3], v[140:141] op_sel:[0,1,0]
	v_pk_fma_f32 v[142:143], v[250:251], v[2:3], v[142:143] op_sel:[0,1,0]
	v_add_f32_dpp v28, v30, v29 row_ror:8 row_mask:0xf bank_mask:0xf
	v_add_f32_dpp v4, v252, v252 quad_perm:[1,0,3,2] row_mask:0xf bank_mask:0xf
	v_add_f32_dpp v5, v253, v253 quad_perm:[1,0,3,2] row_mask:0xf bank_mask:0xf
	v_add_f32_dpp v6, v254, v254 quad_perm:[1,0,3,2] row_mask:0xf bank_mask:0xf
	v_add_f32_dpp v7, v255, v255 quad_perm:[1,0,3,2] row_mask:0xf bank_mask:0xf
	v_cndmask_b32_e32 v4, v6, v4, vcc
	v_cndmask_b32_e32 v5, v7, v5, vcc
	v_add_f32_dpp v10, v8, v8 quad_perm:[2,3,0,1] row_mask:0xf bank_mask:0xf
	v_add_f32_dpp v11, v9, v9 quad_perm:[2,3,0,1] row_mask:0xf bank_mask:0xf
	v_cndmask_b32_e64 v8, v11, v10, s[4:5]
	v_cndmask_b32_e64 v13, v8, v12, s[6:7]
	v_cndmask_b32_e64 v14, v12, v8, s[6:7]
	s_nop 1
	v_add_f32_dpp v12, v14, v13 row_ror:4 row_mask:0xf bank_mask:0xf
	v_add_f32_dpp v0, v140, v140 quad_perm:[1,0,3,2] row_mask:0xf bank_mask:0xf
	v_add_f32_dpp v1, v141, v141 quad_perm:[1,0,3,2] row_mask:0xf bank_mask:0xf
	v_add_f32_dpp v2, v142, v142 quad_perm:[1,0,3,2] row_mask:0xf bank_mask:0xf
	v_add_f32_dpp v3, v143, v143 quad_perm:[1,0,3,2] row_mask:0xf bank_mask:0xf
	v_cndmask_b32_e32 v0, v2, v0, vcc
	v_cndmask_b32_e32 v1, v3, v1, vcc
	v_add_f32_dpp v6, v4, v4 quad_perm:[2,3,0,1] row_mask:0xf bank_mask:0xf
	v_add_f32_dpp v7, v5, v5 quad_perm:[2,3,0,1] row_mask:0xf bank_mask:0xf
	v_cndmask_b32_e64 v4, v7, v6, s[4:5]
	v_add_f32_dpp v2, v0, v0 quad_perm:[2,3,0,1] row_mask:0xf bank_mask:0xf
	v_add_f32_dpp v3, v1, v1 quad_perm:[2,3,0,1] row_mask:0xf bank_mask:0xf
	v_cndmask_b32_e64 v0, v3, v2, s[4:5]
	v_cndmask_b32_e64 v5, v0, v4, s[6:7]
	v_cndmask_b32_e64 v6, v4, v0, s[6:7]
	s_nop 1
	v_add_f32_dpp v4, v6, v5 row_ror:4 row_mask:0xf bank_mask:0xf
	v_cndmask_b32_e64 v13, v4, v12, s[64:65]
	v_cndmask_b32_e64 v14, v12, v4, s[64:65]
	s_nop 1
	v_add_f32_dpp v12, v14, v13 row_ror:8 row_mask:0xf bank_mask:0xf
	s_nop 1
	v_permlane16_swap_b32_e32 v28, v12
	v_add_f32_e32 v28, v28, v12
	s_nop 1
	v_permlane32_swap_b32_e32 v60, v28
	v_add_f32_e32 v60, v60, v28
	ds_write_b32 v235, v60 offset:64
	v_add_u32_e32 v100, v162, v144
	global_load_dwordx4 v[100:103], v100, s[66:67] nt
	v_add_u32_e32 v92, v166, v144
	global_load_dwordx4 v[92:95], v92, s[66:67] nt
	v_add_u32_e32 v112, v168, v144
	global_load_dwordx4 v[112:115], v112, s[66:67] nt
	v_add_u32_e32 v108, v172, v144
	global_load_dwordx4 v[108:111], v108, s[66:67] nt
	v_add_u32_e32 v120, v176, v144
	global_load_dwordx4 v[120:123], v120, s[66:67] nt
	v_add_u32_e32 v116, v180, v144
	global_load_dwordx4 v[116:119], v116, s[66:67] nt
	v_add_u32_e32 v124, v182, v144
	global_load_dwordx4 v[124:127], v124, s[66:67] nt
	v_add_u32_e32 v104, v186, v144
	global_load_dwordx4 v[104:107], v104, s[66:67] nt
	v_add_u32_e32 v68, v190, v144
	global_load_dwordx4 v[68:71], v68, s[66:67] nt
	v_add_u32_e32 v64, v194, v144
	global_load_dwordx4 v[64:67], v64, s[66:67] nt
	v_add_u32_e32 v80, v198, v144
	global_load_dwordx4 v[80:83], v80, s[66:67] nt
	v_add_u32_e32 v76, v200, v144
	global_load_dwordx4 v[76:79], v76, s[66:67] nt
	v_add_u32_e32 v88, v202, v144
	global_load_dwordx4 v[88:91], v88, s[66:67] nt
	v_add_u32_e32 v84, v204, v144
	global_load_dwordx4 v[84:87], v84, s[66:67] nt
	v_add_u32_e32 v96, v206, v144
	global_load_dwordx4 v[96:99], v96, s[66:67] nt
	v_add_u32_e32 v72, v208, v144
	global_load_dwordx4 v[72:75], v72, s[66:67] nt
	v_add_u32_e32 v40, v146, v144
	global_load_dwordx4 v[40:43], v40, s[66:67] nt
	v_add_u32_e32 v36, v148, v144
	global_load_dwordx4 v[36:39], v36, s[66:67] nt
	v_add_u32_e32 v48, v150, v144
	global_load_dwordx4 v[48:51], v48, s[66:67] nt
	v_add_u32_e32 v44, v152, v144
	global_load_dwordx4 v[44:47], v44, s[66:67] nt
	v_add_u32_e32 v56, v154, v144
	global_load_dwordx4 v[56:59], v56, s[66:67] nt
	v_add_u32_e32 v52, v156, v144
	global_load_dwordx4 v[52:55], v52, s[66:67] nt
	v_add_u32_e32 v60, v158, v144
	global_load_dwordx4 v[60:63], v60, s[66:67] nt
	v_add_u32_e32 v32, v160, v144
	global_load_dwordx4 v[32:35], v32, s[66:67] nt
	v_add_u32_e32 v12, v164, v144
	global_load_dwordx4 v[12:15], v12, s[66:67] nt
	v_add_u32_e32 v4, v170, v144
	global_load_dwordx4 v[4:7], v4, s[66:67] nt
	v_add_u32_e32 v20, v174, v144
	global_load_dwordx4 v[20:23], v20, s[66:67] nt
	v_add_u32_e32 v8, v178, v144
	global_load_dwordx4 v[8:11], v8, s[66:67] nt
	v_add_u32_e32 v24, v184, v144
	global_load_dwordx4 v[24:27], v24, s[66:67] nt
	v_add_u32_e32 v16, v188, v144
	global_load_dwordx4 v[16:19], v16, s[66:67] nt
	v_add_u32_e32 v28, v192, v144
	global_load_dwordx4 v[28:31], v28, s[66:67] nt
	v_add_u32_e32 v0, v196, v144
	global_load_dwordx4 v[0:3], v0, s[66:67] nt
	v_lshlrev_b32_e32 v240, 2, v223
	s_waitcnt lgkmcnt(0)
	s_barrier
	v_cmp_gt_i32_e32 vcc, 4, v210
	s_and_saveexec_b64 s[4:5], vcc
	s_cbranch_execz .LBB0_1603

; DI float wave_sum(float v) { for (int o = 32; o >= 1; o >>= 1) v += __shfl_xor(v, o); return v; }
; DI void attn_sample_item(const Params& p, int item, ldsp lds, int tid_) {
;     ...
;   if (wid < 4) {
;     float v[4]; float mx = -1e30f;
; #pragma unroll
;     for (int j = 0; j < 4; ++j) { v[j] = SC[wid * 256 + j * 64 + lane]; mx = fmaxf(mx, v[j]); }
;     for (int o = 32; o >= 1; o >>= 1) mx = fmaxf(mx, __shfl_xor(mx, o));
;     float s = 0.f;
; #pragma unroll
;     for (int j = 0; j < 4; ++j) { v[j] = __expf(v[j] - mx); s += v[j]; }
;     s = wave_sum(s); const float inv = 1.f / s;
; #pragma unroll
;     for (int j = 0; j < 4; ++j) SC[wid * 256 + j * 64 + lane] = v[j] * inv;
;   }
	v_lshlrev_b32_e32 v241, 10, v210
	v_add3_u32 v244, 16, v241, v240
	ds_read2st64_b32 v[240:241], v244 offset1:1
	ds_read2st64_b32 v[242:243], v244 offset0:2 offset1:3
	s_waitcnt lgkmcnt(1)
	v_max3_f32 v245, v240, s39, v241
	s_waitcnt lgkmcnt(0)
	v_max3_f32 v245, v245, v242, v243
	ds_bpermute_b32 v246, v133, v245
	s_waitcnt lgkmcnt(0)
	v_max_f32_e32 v246, v246, v246
	v_max_f32_e32 v245, v245, v246
	ds_bpermute_b32 v246, v132, v245
	s_waitcnt lgkmcnt(0)
	v_max_f32_e32 v246, v246, v246
	v_max_f32_e32 v245, v245, v246
	ds_bpermute_b32 v246, v131, v245
	s_waitcnt lgkmcnt(0)
	v_max_f32_e32 v246, v246, v246
	v_max_f32_e32 v245, v245, v246
	ds_bpermute_b32 v246, v130, v245
	s_waitcnt lgkmcnt(0)
	v_max_f32_e32 v246, v246, v246
	v_max_f32_e32 v245, v245, v246
	ds_bpermute_b32 v246, v129, v245
	s_waitcnt lgkmcnt(0)
	v_max_f32_e32 v246, v246, v246
	v_max_f32_e32 v245, v245, v246
	ds_bpermute_b32 v246, v128, v245
	s_waitcnt lgkmcnt(0)
	v_max_f32_e32 v246, v246, v246
	v_max_f32_e32 v245, v245, v246
	v_sub_f32_e32 v240, v240, v245
	v_sub_f32_e32 v241, v241, v245
	v_mul_f32_e32 v240, 0x3fb8aa3b, v240
	v_sub_f32_e32 v242, v242, v245
	v_mul_f32_e32 v241, 0x3fb8aa3b, v241
	v_exp_f32_e32 v240, v240
	v_sub_f32_e32 v243, v243, v245
	v_mul_f32_e32 v242, 0x3fb8aa3b, v242
	v_exp_f32_e32 v241, v241
	v_mul_f32_e32 v243, 0x3fb8aa3b, v243
	v_exp_f32_e32 v242, v242
	v_exp_f32_e32 v243, v243
	v_add_f32_e32 v245, 0, v240
	v_add_f32_e32 v245, v241, v245
	v_add_f32_e32 v245, v242, v245
	v_add_f32_e32 v245, v243, v245
	ds_bpermute_b32 v246, v133, v245
	s_waitcnt lgkmcnt(0)
	v_add_f32_e32 v245, v245, v246
	ds_bpermute_b32 v246, v132, v245
	s_waitcnt lgkmcnt(0)
	v_add_f32_e32 v245, v245, v246
	ds_bpermute_b32 v246, v131, v245
	s_waitcnt lgkmcnt(0)
	v_add_f32_e32 v245, v245, v246
	ds_bpermute_b32 v246, v130, v245
	s_waitcnt lgkmcnt(0)
	v_add_f32_e32 v245, v245, v246
	ds_bpermute_b32 v246, v129, v245
	s_waitcnt lgkmcnt(0)
	v_add_f32_e32 v245, v245, v246
	ds_bpermute_b32 v246, v128, v245
	s_waitcnt lgkmcnt(0)
	v_add_f32_e32 v245, v245, v246
	v_div_scale_f32 v246, s[6:7], v245, v245, 1.0
	v_rcp_f32_e32 v247, v246
	v_div_scale_f32 v248, vcc, 1.0, v245, 1.0
	v_fma_f32 v249, -v246, v247, 1.0
	v_fmac_f32_e32 v247, v249, v247
	v_mul_f32_e32 v249, v248, v247
	v_fma_f32 v250, -v246, v249, v248
	v_fmac_f32_e32 v249, v250, v247
	v_fma_f32 v246, -v246, v249, v248
	v_div_fmas_f32 v246, v246, v247, v249
	v_div_fixup_f32 v245, v246, v245, 1.0
	v_mul_f32_e32 v240, v240, v245
	v_mul_f32_e32 v241, v241, v245
	v_mul_f32_e32 v242, v242, v245
	v_mul_f32_e32 v243, v243, v245
	ds_write2st64_b32 v244, v240, v241 offset1:1
	ds_write2st64_b32 v244, v242, v243 offset0:2 offset1:3
	s_branch .LBB0_1603

; #define LAS __attribute__((address_space(3)))
; DI void attn_sample_item(const Params& p, int item, ldsp lds, int tid_) {
;     ...
;   const int b = item >> 2, h = item & 3;
;   bf16_t* qx = (bf16_t*)(p.ws + B_QX);
;   const float* ck = p.in[6] + ((size_t)b * 256 * 4 + h) * 256;
;   const float* cv = p.in[7] + ((size_t)b * 256 * 4 + h) * 256;
;   LAS float* SC = (LAS float*)lds;
;   LAS float* PART = (LAS float*)(lds + 4096);
;   float q[4][4];
; #pragma unroll
;   for (int t = 0; t < 4; ++t) { f32x4 a = {0.f, 0.f, 0.f, 0.f}; const float* pp = (const float*)(p.ws + B_PART) + (size_t)(b * 4 + t) * 1024 + h * 256 + lane * 4;
; #pragma unroll
;     for (int kp = 0; kp < 4; ++kp) a += *(const f32x4*)(pp + (size_t)kp * 512 * 1024);
;     q[t][0] = a[0] * 0.0625f; q[t][1] = a[1] * 0.0625f; q[t][2] = a[2] * 0.0625f; q[t][3] = a[3] * 0.0625f; }
;   const bool b0 = lane & 1, b1 = lane & 2;
;   f32x4 kvA[16], kvB[16];
; #pragma unroll
;   for (int j = 0; j < 16; ++j) kvA[j] = __builtin_nontemporal_load((const f32x4*)(ck + (size_t)(wid * 32 + j) * 1024 + lane * 4));
; #pragma unroll
;   for (int j = 0; j < 16; ++j) kvB[j] = __builtin_nontemporal_load((const f32x4*)(ck + (size_t)(wid * 32 + 16 + j) * 1024 + lane * 4));
.LBB0_1676:
	s_ashr_i32 s4, s38, 2
	s_ashr_i32 s5, s4, 31
	s_lshl_b64 s[4:5], s[4:5], 18
	s_and_b32 s24, s0, 0x300
	v_mov_b32_e32 v222, v212
	s_or_b32 s4, s4, s24
	s_and_b32 s26, s38, -4
	s_lshl_b32 s6, s24, 2
	s_add_u32 s6, s36, s6
	v_and_b32_e32 v223, 63, v222
	s_addc_u32 s7, s37, 0
	v_lshlrev_b32_e32 v144, 4, v223
	s_lshl_b64 s[60:61], s[4:5], 2
	s_add_u32 s60, s12, s60
	s_addc_u32 s61, s13, s61
	v_ashrrev_i32_e32 v244, 6, v222
	v_lshlrev_b32_e32 v236, 5, v244
	s_ashr_i32 s27, s26, 31
	v_lshl_add_u64 v[48:49], s[6:7], 0, v[144:145]
	s_lshl_b64 s[6:7], s[26:27], 12
	v_lshl_add_u64 v[8:9], v[48:49], 0, s[6:7]
	v_add_co_u32_e32 v10, vcc, s3, v8
	s_or_b32 s6, s26, 1
	s_nop 0
	v_addc_co_u32_e32 v11, vcc, 0, v9, vcc
	global_load_dwordx4 v[0:3], v[8:9], off
	global_load_dwordx4 v[4:7], v[10:11], off
	v_add_co_u32_e32 v10, vcc, s33, v8
	s_ashr_i32 s7, s6, 31
	s_nop 0
	v_addc_co_u32_e32 v11, vcc, 0, v9, vcc
	v_add_co_u32_e32 v12, vcc, s34, v8
	s_lshl_b64 s[6:7], s[6:7], 12
	s_nop 0
	v_addc_co_u32_e32 v13, vcc, 0, v9, vcc
	v_lshl_add_u64 v[24:25], v[48:49], 0, s[6:7]
	v_add_co_u32_e32 v20, vcc, s3, v24
	s_or_b32 s6, s26, 2
	s_nop 0
	v_addc_co_u32_e32 v21, vcc, 0, v25, vcc
	v_add_co_u32_e32 v26, vcc, s33, v24
	s_ashr_i32 s7, s6, 31
	s_nop 0
	v_addc_co_u32_e32 v27, vcc, 0, v25, vcc
	v_add_co_u32_e32 v28, vcc, s34, v24
	s_lshl_b64 s[6:7], s[6:7], 12
	s_nop 0
	v_addc_co_u32_e32 v29, vcc, 0, v25, vcc
	v_lshl_add_u64 v[44:45], v[48:49], 0, s[6:7]
	global_load_dwordx4 v[8:11], v[10:11], off
	s_nop 0
	global_load_dwordx4 v[12:15], v[12:13], off
	s_nop 0
	global_load_dwordx4 v[16:19], v[24:25], off
	s_nop 0
	global_load_dwordx4 v[20:23], v[20:21], off
	v_add_co_u32_e32 v36, vcc, s3, v44
	global_load_dwordx4 v[24:27], v[26:27], off
	s_nop 0
	global_load_dwordx4 v[28:31], v[28:29], off
	v_addc_co_u32_e32 v37, vcc, 0, v45, vcc
	v_add_co_u32_e32 v40, vcc, s33, v44
	global_load_dwordx4 v[32:35], v[44:45], off
	s_nop 0
	global_load_dwordx4 v[36:39], v[36:37], off
	v_addc_co_u32_e32 v41, vcc, 0, v45, vcc
	v_add_co_u32_e32 v44, vcc, s34, v44
	global_load_dwordx4 v[40:43], v[40:41], off
	s_nop 0
	v_addc_co_u32_e32 v45, vcc, 0, v45, vcc
	global_load_dwordx4 v[44:47], v[44:45], off
	s_or_b32 s6, s38, 3
	s_ashr_i32 s7, s6, 31
	s_lshl_b64 s[6:7], s[6:7], 12
	s_lshl_b64 s[28:29], s[4:5], 2
	s_add_u32 s4, s12, s28
	s_addc_u32 s5, s13, s29
	s_waitcnt vmcnt(11)
	v_pk_add_f32 v[2:3], v[2:3], 0 op_sel_hi:[1,0]
	v_pk_add_f32 v[0:1], v[0:1], 0 op_sel_hi:[1,0]
	s_waitcnt vmcnt(10)
	v_pk_add_f32 v[2:3], v[2:3], v[6:7]
	v_pk_add_f32 v[0:1], v[0:1], v[4:5]
	s_waitcnt vmcnt(9)
	v_pk_add_f32 v[2:3], v[2:3], v[10:11]
	s_waitcnt vmcnt(7)
	v_pk_add_f32 v[4:5], v[18:19], 0 op_sel_hi:[1,0]
	v_pk_add_f32 v[6:7], v[16:17], 0 op_sel_hi:[1,0]
	v_pk_add_f32 v[0:1], v[0:1], v[8:9]
	s_waitcnt vmcnt(6)
	v_pk_add_f32 v[4:5], v[4:5], v[22:23]
	v_pk_add_f32 v[6:7], v[6:7], v[20:21]
	v_pk_add_f32 v[2:3], v[2:3], v[14:15]
	v_pk_add_f32 v[0:1], v[0:1], v[12:13]
	s_waitcnt vmcnt(5)
	v_pk_add_f32 v[4:5], v[4:5], v[26:27]
	v_pk_add_f32 v[6:7], v[6:7], v[24:25]
	v_mul_f32_e32 v228, 0x3d800000, v0
	v_mul_f32_e32 v231, 0x3d800000, v1
	v_mul_f32_e32 v229, 0x3d800000, v2
	v_mul_f32_e32 v225, 0x3d800000, v3
	s_waitcnt vmcnt(4)
	v_pk_add_f32 v[0:1], v[4:5], v[30:31]
	v_pk_add_f32 v[2:3], v[6:7], v[28:29]
	v_mul_f32_e32 v227, 0x3d800000, v0
	v_mul_f32_e32 v226, 0x3d800000, v2
	v_mul_f32_e32 v230, 0x3d800000, v3
	v_mul_f32_e32 v224, 0x3d800000, v1
	s_waitcnt vmcnt(3)
	v_pk_add_f32 v[0:1], v[34:35], 0 op_sel_hi:[1,0]
	v_pk_add_f32 v[2:3], v[32:33], 0 op_sel_hi:[1,0]
	s_waitcnt vmcnt(2)
	v_pk_add_f32 v[0:1], v[0:1], v[38:39]
	v_pk_add_f32 v[2:3], v[2:3], v[36:37]
	s_waitcnt vmcnt(1)
	v_pk_add_f32 v[0:1], v[0:1], v[42:43]
	v_pk_add_f32 v[2:3], v[2:3], v[40:41]
	s_waitcnt vmcnt(0)
	v_pk_add_f32 v[210:211], v[0:1], v[46:47]
	v_pk_add_f32 v[0:1], v[2:3], v[44:45]
	v_mul_f32_e32 v233, 0x3d800000, v210
	v_mul_f32_e32 v232, 0x3d800000, v0
	v_mul_f32_e32 v234, 0x3d800000, v1
	v_lshl_add_u64 v[0:1], v[48:49], 0, s[6:7]
	v_add_co_u32_e32 v2, vcc, s3, v0
	v_ashrrev_i32_e32 v210, 6, v222
	s_nop 0
	v_addc_co_u32_e32 v3, vcc, 0, v1, vcc
	global_load_dwordx4 v[128:131], v[0:1], off
	global_load_dwordx4 v[132:135], v[2:3], off
	v_add_co_u32_e32 v2, vcc, s33, v0
	v_mul_f32_e32 v211, 0x3d800000, v211
	s_nop 0
	v_addc_co_u32_e32 v3, vcc, 0, v1, vcc
	v_add_co_u32_e32 v0, vcc, s34, v0
	v_cmp_lt_i32_e64 s[6:7], v218, v216
	s_nop 0
	v_addc_co_u32_e32 v1, vcc, 0, v1, vcc
	global_load_dwordx4 v[136:139], v[2:3], off
	global_load_dwordx4 v[140:143], v[0:1], off
	v_add_u32_e32 v240, 0, v244
	v_lshlrev_b32_e32 v158, 12, v240
	v_mov_b32_e32 v159, 0
	v_add_u32_e32 v124, v158, v144
	global_load_dwordx4 v[124:127], v124, s[60:61] nt
	v_add_u32_e32 v240, 8, v244
	v_lshlrev_b32_e32 v162, 12, v240
	v_mov_b32_e32 v163, 0
	v_add_u32_e32 v120, v162, v144
	global_load_dwordx4 v[120:123], v120, s[60:61] nt
	v_add_u32_e32 v240, 16, v244
	v_lshlrev_b32_e32 v164, 12, v240
	v_mov_b32_e32 v165, 0
	v_add_u32_e32 v116, v164, v144
	global_load_dwordx4 v[116:119], v116, s[60:61] nt
	v_add_u32_e32 v240, 24, v244
	v_lshlrev_b32_e32 v168, 12, v240
	v_mov_b32_e32 v169, 0
	v_add_u32_e32 v112, v168, v144
	global_load_dwordx4 v[112:115], v112, s[60:61] nt
	v_add_u32_e32 v240, 32, v244
	v_lshlrev_b32_e32 v172, 12, v240
	v_mov_b32_e32 v173, 0
	v_add_u32_e32 v108, v172, v144
	global_load_dwordx4 v[108:111], v108, s[60:61] nt
	v_add_u32_e32 v240, 40, v244
	v_lshlrev_b32_e32 v176, 12, v240
	v_mov_b32_e32 v177, 0
	v_add_u32_e32 v104, v176, v144
	global_load_dwordx4 v[104:107], v104, s[60:61] nt
	v_add_u32_e32 v240, 48, v244
	v_lshlrev_b32_e32 v180, 12, v240
	v_mov_b32_e32 v181, 0
; DI void attn_sample_item(const Params& p, int item, ldsp lds, int tid_) {
;     ...
;   for (int j = 0; j < 16; ++j) kvA[j] = __builtin_nontemporal_load((const f32x4*)(ck + (size_t)(wid * 32 + j) * 1024 + lane * 4));
; #pragma unroll
;   for (int j = 0; j < 16; ++j) kvB[j] = __builtin_nontemporal_load((const f32x4*)(ck + (size_t)(wid * 32 + 16 + j) * 1024 + lane * 4));
	v_add_u32_e32 v100, v180, v144
	global_load_dwordx4 v[100:103], v100, s[60:61] nt
	v_add_u32_e32 v240, 56, v244
	v_lshlrev_b32_e32 v184, 12, v240
	v_mov_b32_e32 v185, 0
	v_add_u32_e32 v96, v184, v144
	global_load_dwordx4 v[96:99], v96, s[60:61] nt
	v_add_u32_e32 v240, 64, v244
	v_lshlrev_b32_e32 v188, 12, v240
	v_mov_b32_e32 v189, 0
	v_add_u32_e32 v92, v188, v144
	global_load_dwordx4 v[92:95], v92, s[60:61] nt
	v_add_u32_e32 v240, 72, v244
	v_lshlrev_b32_e32 v192, 12, v240
	v_mov_b32_e32 v193, 0
	v_add_u32_e32 v88, v192, v144
	global_load_dwordx4 v[88:91], v88, s[60:61] nt
	v_add_u32_e32 v240, 80, v244
	v_lshlrev_b32_e32 v196, 12, v240
	v_mov_b32_e32 v197, 0
	v_add_u32_e32 v84, v196, v144
	global_load_dwordx4 v[84:87], v84, s[60:61] nt
	v_add_u32_e32 v240, 88, v244
	v_lshlrev_b32_e32 v200, 12, v240
	v_mov_b32_e32 v201, 0
	v_add_u32_e32 v80, v200, v144
	global_load_dwordx4 v[80:83], v80, s[60:61] nt
	v_add_u32_e32 v240, 96, v244
	v_lshlrev_b32_e32 v202, 12, v240
	v_mov_b32_e32 v203, 0
	v_add_u32_e32 v76, v202, v144
	global_load_dwordx4 v[76:79], v76, s[60:61] nt
	v_add_u32_e32 v240, 104, v244
	v_lshlrev_b32_e32 v204, 12, v240
	v_mov_b32_e32 v205, 0
	v_add_u32_e32 v72, v204, v144
	global_load_dwordx4 v[72:75], v72, s[60:61] nt
	v_add_u32_e32 v240, 112, v244
	v_lshlrev_b32_e32 v206, 12, v240
	v_mov_b32_e32 v207, 0
	v_add_u32_e32 v68, v206, v144
	global_load_dwordx4 v[68:71], v68, s[60:61] nt
	v_add_u32_e32 v240, 120, v244
	v_lshlrev_b32_e32 v208, 12, v240
	v_mov_b32_e32 v209, 0
	v_add_u32_e32 v64, v208, v144
	global_load_dwordx4 v[64:67], v64, s[60:61] nt
	v_add_u32_e32 v240, 128, v244
	v_lshlrev_b32_e32 v146, 12, v240
	v_mov_b32_e32 v147, 0
	v_add_u32_e32 v60, v146, v144
	global_load_dwordx4 v[60:63], v60, s[60:61] nt
	v_add_u32_e32 v240, 136, v244
	v_lshlrev_b32_e32 v148, 12, v240
	v_mov_b32_e32 v149, 0
	v_add_u32_e32 v56, v148, v144
	global_load_dwordx4 v[56:59], v56, s[60:61] nt
	v_add_u32_e32 v240, 144, v244
	v_lshlrev_b32_e32 v150, 12, v240
	v_mov_b32_e32 v151, 0
	v_add_u32_e32 v52, v150, v144
	global_load_dwordx4 v[52:55], v52, s[60:61] nt
	v_add_u32_e32 v240, 152, v244
	v_lshlrev_b32_e32 v152, 12, v240
	v_mov_b32_e32 v153, 0
	v_add_u32_e32 v48, v152, v144
	global_load_dwordx4 v[48:51], v48, s[60:61] nt
	v_add_u32_e32 v240, 160, v244
	v_lshlrev_b32_e32 v154, 12, v240
	v_mov_b32_e32 v155, 0
	v_add_u32_e32 v44, v154, v144
	global_load_dwordx4 v[44:47], v44, s[60:61] nt
	v_add_u32_e32 v240, 168, v244
	v_lshlrev_b32_e32 v156, 12, v240
	v_mov_b32_e32 v157, 0
	v_add_u32_e32 v40, v156, v144
	global_load_dwordx4 v[40:43], v40, s[60:61] nt
	v_add_u32_e32 v240, 176, v244
	v_lshlrev_b32_e32 v160, 12, v240
	v_mov_b32_e32 v161, 0
	v_add_u32_e32 v36, v160, v144
	global_load_dwordx4 v[36:39], v36, s[60:61] nt
	v_add_u32_e32 v240, 184, v244
	v_lshlrev_b32_e32 v166, 12, v240
	v_mov_b32_e32 v167, 0
	v_add_u32_e32 v32, v166, v144
	global_load_dwordx4 v[32:35], v32, s[60:61] nt
	v_add_u32_e32 v240, 192, v244
	v_lshlrev_b32_e32 v170, 12, v240
	v_mov_b32_e32 v171, 0
	v_add_u32_e32 v28, v170, v144
	global_load_dwordx4 v[28:31], v28, s[60:61] nt
	v_add_u32_e32 v240, 200, v244
	v_lshlrev_b32_e32 v174, 12, v240
	v_mov_b32_e32 v175, 0
	v_add_u32_e32 v24, v174, v144
	global_load_dwordx4 v[24:27], v24, s[60:61] nt
	v_add_u32_e32 v240, 208, v244
	v_lshlrev_b32_e32 v178, 12, v240
	v_mov_b32_e32 v179, 0
	v_add_u32_e32 v20, v178, v144
	global_load_dwordx4 v[20:23], v20, s[60:61] nt
	v_add_u32_e32 v240, 216, v244
	v_lshlrev_b32_e32 v182, 12, v240
	v_mov_b32_e32 v183, 0
	v_add_u32_e32 v16, v182, v144
	global_load_dwordx4 v[16:19], v16, s[60:61] nt
	v_add_u32_e32 v240, 224, v244
	v_lshlrev_b32_e32 v186, 12, v240
	v_mov_b32_e32 v187, 0
	v_add_u32_e32 v12, v186, v144
	global_load_dwordx4 v[12:15], v12, s[60:61] nt
	v_add_u32_e32 v240, 232, v244
	v_lshlrev_b32_e32 v190, 12, v240
	v_mov_b32_e32 v191, 0
	v_add_u32_e32 v8, v190, v144
	global_load_dwordx4 v[8:11], v8, s[60:61] nt
	v_add_u32_e32 v240, 240, v244
	v_lshlrev_b32_e32 v194, 12, v240
	v_mov_b32_e32 v195, 0
	v_add_u32_e32 v4, v194, v144
	global_load_dwordx4 v[4:7], v4, s[60:61] nt
	v_add_u32_e32 v240, 248, v244
	v_lshlrev_b32_e32 v198, 12, v240
	v_mov_b32_e32 v199, 0
	v_add_u32_e32 v0, v198, v144
	global_load_dwordx4 v[0:3], v0, s[60:61] nt
	s_waitcnt vmcnt(35)
	v_pk_add_f32 v[128:129], v[128:129], 0 op_sel_hi:[1,0]
	v_pk_add_f32 v[130:131], v[130:131], 0 op_sel_hi:[1,0]
	s_waitcnt vmcnt(34)
	v_pk_add_f32 v[128:129], v[128:129], v[132:133]
	v_pk_add_f32 v[130:131], v[130:131], v[134:135]
	s_waitcnt vmcnt(33)
	v_pk_add_f32 v[128:129], v[128:129], v[136:137]
	v_pk_add_f32 v[130:131], v[130:131], v[138:139]
	s_waitcnt vmcnt(32)
	v_pk_add_f32 v[128:129], v[128:129], v[140:141]
	v_pk_add_f32 v[130:131], v[130:131], v[142:143]
	v_mul_f32_e32 v138, 0x3d800000, v129
	v_mul_f32_e32 v135, 0x3d800000, v128
	v_mul_f32_e32 v134, 0x3d800000, v131
	s_add_u32 s66, s14, s28
	s_addc_u32 s67, s15, s29
	v_mul_f32_e32 v137, 0x3d800000, v130
	v_lshlrev_b32_e32 v128, 2, v215
	v_lshlrev_b32_e32 v129, 2, v217
	v_lshlrev_b32_e32 v130, 2, v218
	v_lshlrev_b32_e32 v131, 2, v219
	v_lshlrev_b32_e32 v132, 2, v220
	v_lshlrev_b32_e32 v133, 2, v221
	v_lshl_add_u32 v136, v210, 7, 16
	v_and_b32_e32 v139, 3, v223
	v_bfrev_b32_e32 v139, v139
	v_lshrrev_b32_e32 v139, 20, v139
	v_and_b32_e32 v235, -4, v223
	v_add3_u32 v235, v136, v139, v235
	v_mov_b32_e32 v236, v228
	v_mov_b32_e32 v237, v226
	v_mov_b32_e32 v238, v231
	v_mov_b32_e32 v239, v230
	v_mov_b32_e32 v240, v229
	v_mov_b32_e32 v241, v227
	v_mov_b32_e32 v242, v225
	v_mov_b32_e32 v243, v224
	v_mov_b32_e32 v244, v232
	v_mov_b32_e32 v245, v135
	v_mov_b32_e32 v246, v234
	v_mov_b32_e32 v247, v138
	v_mov_b32_e32 v248, v233
	v_mov_b32_e32 v249, v137
	v_mov_b32_e32 v250, v211
	v_mov_b32_e32 v251, v134
	s_mov_b32 vcc_lo, 0x55555555
	s_mov_b32 vcc_hi, 0x55555555
	s_mov_b32 s4, 0x33333333
	s_mov_b32 s5, 0x33333333
	s_mov_b32 s6, 0x0f0f0f0f
	s_mov_b32 s7, 0x0f0f0f0f
	s_mov_b32 s64, 0x00ff00ff
	s_mov_b32 s65, 0x00ff00ff
	s_waitcnt vmcnt(31)
	v_pk_mul_f32 v[252:253], v[236:237], v[124:125] op_sel_hi:[1,0]
	v_pk_mul_f32 v[254:255], v[244:245], v[124:125] op_sel_hi:[1,0]
	v_pk_fma_f32 v[252:253], v[238:239], v[124:125], v[252:253] op_sel:[0,1,0]
	v_pk_fma_f32 v[254:255], v[246:247], v[124:125], v[254:255] op_sel:[0,1,0]
	v_pk_fma_f32 v[252:253], v[240:241], v[126:127], v[252:253] op_sel_hi:[1,0,1]
	v_pk_fma_f32 v[254:255], v[248:249], v[126:127], v[254:255] op_sel_hi:[1,0,1]
	v_pk_fma_f32 v[252:253], v[242:243], v[126:127], v[252:253] op_sel:[0,1,0]
	v_pk_fma_f32 v[254:255], v[250:251], v[126:127], v[254:255] op_sel:[0,1,0]
	s_waitcnt vmcnt(30)
	v_pk_mul_f32 v[140:141], v[236:237], v[120:121] op_sel_hi:[1,0]
	v_pk_mul_f32 v[142:143], v[244:245], v[120:121] op_sel_hi:[1,0]
	v_pk_fma_f32 v[140:141], v[238:239], v[120:121], v[140:141] op_sel:[0,1,0]
	v_pk_fma_f32 v[142:143], v[246:247], v[120:121], v[142:143] op_sel:[0,1,0]
	v_pk_fma_f32 v[140:141], v[240:241], v[122:123], v[140:141] op_sel_hi:[1,0,1]
	v_pk_fma_f32 v[142:143], v[248:249], v[122:123], v[142:143] op_sel_hi:[1,0,1]
	v_pk_fma_f32 v[140:141], v[242:243], v[122:123], v[140:141] op_sel:[0,1,0]
	v_pk_fma_f32 v[142:143], v[250:251], v[122:123], v[142:143] op_sel:[0,1,0]
	v_add_f32_dpp v124, v252, v252 quad_perm:[1,0,3,2] row_mask:0xf bank_mask:0xf
	v_add_f32_dpp v125, v253, v253 quad_perm:[1,0,3,2] row_mask:0xf bank_mask:0xf
	v_add_f32_dpp v126, v254, v254 quad_perm:[1,0,3,2] row_mask:0xf bank_mask:0xf
	v_add_f32_dpp v127, v255, v255 quad_perm:[1,0,3,2] row_mask:0xf bank_mask:0xf
	v_cndmask_b32_e32 v124, v126, v124, vcc
	v_cndmask_b32_e32 v125, v127, v125, vcc
	s_waitcnt vmcnt(29)
	v_pk_mul_f32 v[252:253], v[236:237], v[116:117] op_sel_hi:[1,0]
	v_pk_mul_f32 v[254:255], v[244:245], v[116:117] op_sel_hi:[1,0]
	v_pk_fma_f32 v[252:253], v[238:239], v[116:117], v[252:253] op_sel:[0,1,0]
	v_pk_fma_f32 v[254:255], v[246:247], v[116:117], v[254:255] op_sel:[0,1,0]
	v_pk_fma_f32 v[252:253], v[240:241], v[118:119], v[252:253] op_sel_hi:[1,0,1]
	v_pk_fma_f32 v[254:255], v[248:249], v[118:119], v[254:255] op_sel_hi:[1,0,1]
	v_pk_fma_f32 v[252:253], v[242:243], v[118:119], v[252:253] op_sel:[0,1,0]
	v_pk_fma_f32 v[254:255], v[250:251], v[118:119], v[254:255] op_sel:[0,1,0]
	v_add_f32_dpp v120, v140, v140 quad_perm:[1,0,3,2] row_mask:0xf bank_mask:0xf
	v_add_f32_dpp v121, v141, v141 quad_perm:[1,0,3,2] row_mask:0xf bank_mask:0xf
	v_add_f32_dpp v122, v142, v142 quad_perm:[1,0,3,2] row_mask:0xf bank_mask:0xf
	v_add_f32_dpp v123, v143, v143 quad_perm:[1,0,3,2] row_mask:0xf bank_mask:0xf
	v_cndmask_b32_e32 v120, v122, v120, vcc
	v_cndmask_b32_e32 v121, v123, v121, vcc
	v_add_f32_dpp v126, v124, v124 quad_perm:[2,3,0,1] row_mask:0xf bank_mask:0xf
	v_add_f32_dpp v127, v125, v125 quad_perm:[2,3,0,1] row_mask:0xf bank_mask:0xf
	v_cndmask_b32_e64 v124, v127, v126, s[4:5]
	s_waitcnt vmcnt(28)
	v_pk_mul_f32 v[140:141], v[236:237], v[112:113] op_sel_hi:[1,0]
	v_pk_mul_f32 v[142:143], v[244:245], v[112:113] op_sel_hi:[1,0]
	v_pk_fma_f32 v[140:141], v[238:239], v[112:113], v[140:141] op_sel:[0,1,0]
	v_pk_fma_f32 v[142:143], v[246:247], v[112:113], v[142:143] op_sel:[0,1,0]
	v_pk_fma_f32 v[140:141], v[240:241], v[114:115], v[140:141] op_sel_hi:[1,0,1]
	v_pk_fma_f32 v[142:143], v[248:249], v[114:115], v[142:143] op_sel_hi:[1,0,1]
	v_pk_fma_f32 v[140:141], v[242:243], v[114:115], v[140:141] op_sel:[0,1,0]
	v_pk_fma_f32 v[142:143], v[250:251], v[114:115], v[142:143] op_sel:[0,1,0]
	v_add_f32_dpp v116, v252, v252 quad_perm:[1,0,3,2] row_mask:0xf bank_mask:0xf
	v_add_f32_dpp v117, v253, v253 quad_perm:[1,0,3,2] row_mask:0xf bank_mask:0xf
	v_add_f32_dpp v118, v254, v254 quad_perm:[1,0,3,2] row_mask:0xf bank_mask:0xf
	v_add_f32_dpp v119, v255, v255 quad_perm:[1,0,3,2] row_mask:0xf bank_mask:0xf
	v_cndmask_b32_e32 v116, v118, v116, vcc
	v_cndmask_b32_e32 v117, v119, v117, vcc
	v_add_f32_dpp v122, v120, v120 quad_perm:[2,3,0,1] row_mask:0xf bank_mask:0xf
	v_add_f32_dpp v123, v121, v121 quad_perm:[2,3,0,1] row_mask:0xf bank_mask:0xf
	v_cndmask_b32_e64 v120, v123, v122, s[4:5]
	v_cndmask_b32_e64 v125, v120, v124, s[6:7]
	v_cndmask_b32_e64 v126, v124, v120, s[6:7]
	s_waitcnt vmcnt(27)
	v_pk_mul_f32 v[252:253], v[236:237], v[108:109] op_sel_hi:[1,0]
	v_pk_mul_f32 v[254:255], v[244:245], v[108:109] op_sel_hi:[1,0]
	v_pk_fma_f32 v[252:253], v[238:239], v[108:109], v[252:253] op_sel:[0,1,0]
	v_pk_fma_f32 v[254:255], v[246:247], v[108:109], v[254:255] op_sel:[0,1,0]
	v_pk_fma_f32 v[252:253], v[240:241], v[110:111], v[252:253] op_sel_hi:[1,0,1]
	v_pk_fma_f32 v[254:255], v[248:249], v[110:111], v[254:255] op_sel_hi:[1,0,1]
	v_pk_fma_f32 v[252:253], v[242:243], v[110:111], v[252:253] op_sel:[0,1,0]
	v_pk_fma_f32 v[254:255], v[250:251], v[110:111], v[254:255] op_sel:[0,1,0]
	v_add_f32_dpp v124, v126, v125 row_ror:4 row_mask:0xf bank_mask:0xf
	v_add_f32_dpp v112, v140, v140 quad_perm:[1,0,3,2] row_mask:0xf bank_mask:0xf
	v_add_f32_dpp v113, v141, v141 quad_perm:[1,0,3,2] row_mask:0xf bank_mask:0xf
	v_add_f32_dpp v114, v142, v142 quad_perm:[1,0,3,2] row_mask:0xf bank_mask:0xf
	v_add_f32_dpp v115, v143, v143 quad_perm:[1,0,3,2] row_mask:0xf bank_mask:0xf
	v_cndmask_b32_e32 v112, v114, v112, vcc
	v_cndmask_b32_e32 v113, v115, v113, vcc
	v_add_f32_dpp v118, v116, v116 quad_perm:[2,3,0,1] row_mask:0xf bank_mask:0xf
	v_add_f32_dpp v119, v117, v117 quad_perm:[2,3,0,1] row_mask:0xf bank_mask:0xf
	v_cndmask_b32_e64 v116, v119, v118, s[4:5]
	s_waitcnt vmcnt(26)
	v_pk_mul_f32 v[140:141], v[236:237], v[104:105] op_sel_hi:[1,0]
	v_pk_mul_f32 v[142:143], v[244:245], v[104:105] op_sel_hi:[1,0]
	v_pk_fma_f32 v[140:141], v[238:239], v[104:105], v[140:141] op_sel:[0,1,0]
	v_pk_fma_f32 v[142:143], v[246:247], v[104:105], v[142:143] op_sel:[0,1,0]
	v_pk_fma_f32 v[140:141], v[240:241], v[106:107], v[140:141] op_sel_hi:[1,0,1]
	v_pk_fma_f32 v[142:143], v[248:249], v[106:107], v[142:143] op_sel_hi:[1,0,1]
	v_pk_fma_f32 v[140:141], v[242:243], v[106:107], v[140:141] op_sel:[0,1,0]
	v_pk_fma_f32 v[142:143], v[250:251], v[106:107], v[142:143] op_sel:[0,1,0]
	v_add_f32_dpp v108, v252, v252 quad_perm:[1,0,3,2] row_mask:0xf bank_mask:0xf
	v_add_f32_dpp v109, v253, v253 quad_perm:[1,0,3,2] row_mask:0xf bank_mask:0xf
	v_add_f32_dpp v110, v254, v254 quad_perm:[1,0,3,2] row_mask:0xf bank_mask:0xf
	v_add_f32_dpp v111, v255, v255 quad_perm:[1,0,3,2] row_mask:0xf bank_mask:0xf
	v_cndmask_b32_e32 v108, v110, v108, vcc
	v_cndmask_b32_e32 v109, v111, v109, vcc
	v_add_f32_dpp v114, v112, v112 quad_perm:[2,3,0,1] row_mask:0xf bank_mask:0xf
	v_add_f32_dpp v115, v113, v113 quad_perm:[2,3,0,1] row_mask:0xf bank_mask:0xf
	v_cndmask_b32_e64 v112, v115, v114, s[4:5]
	v_cndmask_b32_e64 v117, v112, v116, s[6:7]
	v_cndmask_b32_e64 v118, v116, v112, s[6:7]
	s_waitcnt vmcnt(25)
	v_pk_mul_f32 v[252:253], v[236:237], v[100:101] op_sel_hi:[1,0]
	v_pk_mul_f32 v[254:255], v[244:245], v[100:101] op_sel_hi:[1,0]
	v_pk_fma_f32 v[252:253], v[238:239], v[100:101], v[252:253] op_sel:[0,1,0]
	v_pk_fma_f32 v[254:255], v[246:247], v[100:101], v[254:255] op_sel:[0,1,0]
	v_pk_fma_f32 v[252:253], v[240:241], v[102:103], v[252:253] op_sel_hi:[1,0,1]
	v_pk_fma_f32 v[254:255], v[248:249], v[102:103], v[254:255] op_sel_hi:[1,0,1]
	v_pk_fma_f32 v[252:253], v[242:243], v[102:103], v[252:253] op_sel:[0,1,0]
	v_pk_fma_f32 v[254:255], v[250:251], v[102:103], v[254:255] op_sel:[0,1,0]
	v_add_f32_dpp v116, v118, v117 row_ror:4 row_mask:0xf bank_mask:0xf
	v_cndmask_b32_e64 v125, v116, v124, s[64:65]
	v_cndmask_b32_e64 v126, v124, v116, s[64:65]
	v_add_f32_dpp v104, v140, v140 quad_perm:[1,0,3,2] row_mask:0xf bank_mask:0xf
	v_add_f32_dpp v105, v141, v141 quad_perm:[1,0,3,2] row_mask:0xf bank_mask:0xf
	v_add_f32_dpp v106, v142, v142 quad_perm:[1,0,3,2] row_mask:0xf bank_mask:0xf
	v_add_f32_dpp v107, v143, v143 quad_perm:[1,0,3,2] row_mask:0xf bank_mask:0xf
	v_cndmask_b32_e32 v104, v106, v104, vcc
	v_cndmask_b32_e32 v105, v107, v105, vcc
	v_add_f32_dpp v110, v108, v108 quad_perm:[2,3,0,1] row_mask:0xf bank_mask:0xf
	v_add_f32_dpp v111, v109, v109 quad_perm:[2,3,0,1] row_mask:0xf bank_mask:0xf
	v_cndmask_b32_e64 v108, v111, v110, s[4:5]
	s_waitcnt vmcnt(24)
	v_pk_mul_f32 v[140:141], v[236:237], v[96:97] op_sel_hi:[1,0]
	v_pk_mul_f32 v[142:143], v[244:245], v[96:97] op_sel_hi:[1,0]
	v_pk_fma_f32 v[140:141], v[238:239], v[96:97], v[140:141] op_sel:[0,1,0]
	v_pk_fma_f32 v[142:143], v[246:247], v[96:97], v[142:143] op_sel:[0,1,0]
	v_pk_fma_f32 v[140:141], v[240:241], v[98:99], v[140:141] op_sel_hi:[1,0,1]
	v_pk_fma_f32 v[142:143], v[248:249], v[98:99], v[142:143] op_sel_hi:[1,0,1]
	v_pk_fma_f32 v[140:141], v[242:243], v[98:99], v[140:141] op_sel:[0,1,0]
	v_pk_fma_f32 v[142:143], v[250:251], v[98:99], v[142:143] op_sel:[0,1,0]
	v_add_f32_dpp v124, v126, v125 row_ror:8 row_mask:0xf bank_mask:0xf
	v_add_f32_dpp v100, v252, v252 quad_perm:[1,0,3,2] row_mask:0xf bank_mask:0xf
	v_add_f32_dpp v101, v253, v253 quad_perm:[1,0,3,2] row_mask:0xf bank_mask:0xf
	v_add_f32_dpp v102, v254, v254 quad_perm:[1,0,3,2] row_mask:0xf bank_mask:0xf
	v_add_f32_dpp v103, v255, v255 quad_perm:[1,0,3,2] row_mask:0xf bank_mask:0xf
	v_cndmask_b32_e32 v100, v102, v100, vcc
	v_cndmask_b32_e32 v101, v103, v101, vcc
	v_add_f32_dpp v106, v104, v104 quad_perm:[2,3,0,1] row_mask:0xf bank_mask:0xf
	v_add_f32_dpp v107, v105, v105 quad_perm:[2,3,0,1] row_mask:0xf bank_mask:0xf
	v_cndmask_b32_e64 v104, v107, v106, s[4:5]
	v_cndmask_b32_e64 v109, v104, v108, s[6:7]
	v_cndmask_b32_e64 v110, v108, v104, s[6:7]
	s_waitcnt vmcnt(23)
	v_pk_mul_f32 v[252:253], v[236:237], v[92:93] op_sel_hi:[1,0]
	v_pk_mul_f32 v[254:255], v[244:245], v[92:93] op_sel_hi:[1,0]
	v_pk_fma_f32 v[252:253], v[238:239], v[92:93], v[252:253] op_sel:[0,1,0]
	v_pk_fma_f32 v[254:255], v[246:247], v[92:93], v[254:255] op_sel:[0,1,0]
	v_pk_fma_f32 v[252:253], v[240:241], v[94:95], v[252:253] op_sel_hi:[1,0,1]
	v_pk_fma_f32 v[254:255], v[248:249], v[94:95], v[254:255] op_sel_hi:[1,0,1]
	v_pk_fma_f32 v[252:253], v[242:243], v[94:95], v[252:253] op_sel:[0,1,0]
	v_pk_fma_f32 v[254:255], v[250:251], v[94:95], v[254:255] op_sel:[0,1,0]
	v_add_f32_dpp v108, v110, v109 row_ror:4 row_mask:0xf bank_mask:0xf
	v_add_f32_dpp v96, v140, v140 quad_perm:[1,0,3,2] row_mask:0xf bank_mask:0xf
	v_add_f32_dpp v97, v141, v141 quad_perm:[1,0,3,2] row_mask:0xf bank_mask:0xf
	v_add_f32_dpp v98, v142, v142 quad_perm:[1,0,3,2] row_mask:0xf bank_mask:0xf
	v_add_f32_dpp v99, v143, v143 quad_perm:[1,0,3,2] row_mask:0xf bank_mask:0xf
	v_cndmask_b32_e32 v96, v98, v96, vcc
	v_cndmask_b32_e32 v97, v99, v97, vcc
	v_add_f32_dpp v102, v100, v100 quad_perm:[2,3,0,1] row_mask:0xf bank_mask:0xf
	v_add_f32_dpp v103, v101, v101 quad_perm:[2,3,0,1] row_mask:0xf bank_mask:0xf
	v_cndmask_b32_e64 v100, v103, v102, s[4:5]
	s_waitcnt vmcnt(22)
	v_pk_mul_f32 v[140:141], v[236:237], v[88:89] op_sel_hi:[1,0]
	v_pk_mul_f32 v[142:143], v[244:245], v[88:89] op_sel_hi:[1,0]
	v_pk_fma_f32 v[140:141], v[238:239], v[88:89], v[140:141] op_sel:[0,1,0]
	v_pk_fma_f32 v[142:143], v[246:247], v[88:89], v[142:143] op_sel:[0,1,0]
	v_pk_fma_f32 v[140:141], v[240:241], v[90:91], v[140:141] op_sel_hi:[1,0,1]
	v_pk_fma_f32 v[142:143], v[248:249], v[90:91], v[142:143] op_sel_hi:[1,0,1]
	v_pk_fma_f32 v[140:141], v[242:243], v[90:91], v[140:141] op_sel:[0,1,0]
	v_pk_fma_f32 v[142:143], v[250:251], v[90:91], v[142:143] op_sel:[0,1,0]
	v_add_f32_dpp v92, v252, v252 quad_perm:[1,0,3,2] row_mask:0xf bank_mask:0xf
	v_add_f32_dpp v93, v253, v253 quad_perm:[1,0,3,2] row_mask:0xf bank_mask:0xf
	v_add_f32_dpp v94, v254, v254 quad_perm:[1,0,3,2] row_mask:0xf bank_mask:0xf
	v_add_f32_dpp v95, v255, v255 quad_perm:[1,0,3,2] row_mask:0xf bank_mask:0xf
	v_cndmask_b32_e32 v92, v94, v92, vcc
	v_cndmask_b32_e32 v93, v95, v93, vcc
	v_add_f32_dpp v98, v96, v96 quad_perm:[2,3,0,1] row_mask:0xf bank_mask:0xf
	v_add_f32_dpp v99, v97, v97 quad_perm:[2,3,0,1] row_mask:0xf bank_mask:0xf
	v_cndmask_b32_e64 v96, v99, v98, s[4:5]
	v_cndmask_b32_e64 v101, v96, v100, s[6:7]
	v_cndmask_b32_e64 v102, v100, v96, s[6:7]
	s_waitcnt vmcnt(21)
	v_pk_mul_f32 v[252:253], v[236:237], v[84:85] op_sel_hi:[1,0]
	v_pk_mul_f32 v[254:255], v[244:245], v[84:85] op_sel_hi:[1,0]
	v_pk_fma_f32 v[252:253], v[238:239], v[84:85], v[252:253] op_sel:[0,1,0]
	v_pk_fma_f32 v[254:255], v[246:247], v[84:85], v[254:255] op_sel:[0,1,0]
	v_pk_fma_f32 v[252:253], v[240:241], v[86:87], v[252:253] op_sel_hi:[1,0,1]
	v_pk_fma_f32 v[254:255], v[248:249], v[86:87], v[254:255] op_sel_hi:[1,0,1]
	v_pk_fma_f32 v[252:253], v[242:243], v[86:87], v[252:253] op_sel:[0,1,0]
	v_pk_fma_f32 v[254:255], v[250:251], v[86:87], v[254:255] op_sel:[0,1,0]
	v_add_f32_dpp v100, v102, v101 row_ror:4 row_mask:0xf bank_mask:0xf
	v_cndmask_b32_e64 v109, v100, v108, s[64:65]
	v_cndmask_b32_e64 v110, v108, v100, s[64:65]
	v_add_f32_dpp v88, v140, v140 quad_perm:[1,0,3,2] row_mask:0xf bank_mask:0xf
	v_add_f32_dpp v89, v141, v141 quad_perm:[1,0,3,2] row_mask:0xf bank_mask:0xf
	v_add_f32_dpp v90, v142, v142 quad_perm:[1,0,3,2] row_mask:0xf bank_mask:0xf
	v_add_f32_dpp v91, v143, v143 quad_perm:[1,0,3,2] row_mask:0xf bank_mask:0xf
	v_cndmask_b32_e32 v88, v90, v88, vcc
	v_cndmask_b32_e32 v89, v91, v89, vcc
	v_add_f32_dpp v94, v92, v92 quad_perm:[2,3,0,1] row_mask:0xf bank_mask:0xf
	v_add_f32_dpp v95, v93, v93 quad_perm:[2,3,0,1] row_mask:0xf bank_mask:0xf
	v_cndmask_b32_e64 v92, v95, v94, s[4:5]
	s_waitcnt vmcnt(20)
	v_pk_mul_f32 v[140:141], v[236:237], v[80:81] op_sel_hi:[1,0]
	v_pk_mul_f32 v[142:143], v[244:245], v[80:81] op_sel_hi:[1,0]
	v_pk_fma_f32 v[140:141], v[238:239], v[80:81], v[140:141] op_sel:[0,1,0]
	v_pk_fma_f32 v[142:143], v[246:247], v[80:81], v[142:143] op_sel:[0,1,0]
	v_pk_fma_f32 v[140:141], v[240:241], v[82:83], v[140:141] op_sel_hi:[1,0,1]
	v_pk_fma_f32 v[142:143], v[248:249], v[82:83], v[142:143] op_sel_hi:[1,0,1]
	v_pk_fma_f32 v[140:141], v[242:243], v[82:83], v[140:141] op_sel:[0,1,0]
	v_pk_fma_f32 v[142:143], v[250:251], v[82:83], v[142:143] op_sel:[0,1,0]
	v_add_f32_dpp v108, v110, v109 row_ror:8 row_mask:0xf bank_mask:0xf
	v_add_f32_dpp v84, v252, v252 quad_perm:[1,0,3,2] row_mask:0xf bank_mask:0xf
	v_add_f32_dpp v85, v253, v253 quad_perm:[1,0,3,2] row_mask:0xf bank_mask:0xf
	v_add_f32_dpp v86, v254, v254 quad_perm:[1,0,3,2] row_mask:0xf bank_mask:0xf
	v_add_f32_dpp v87, v255, v255 quad_perm:[1,0,3,2] row_mask:0xf bank_mask:0xf
	v_cndmask_b32_e32 v84, v86, v84, vcc
	v_cndmask_b32_e32 v85, v87, v85, vcc
	v_add_f32_dpp v90, v88, v88 quad_perm:[2,3,0,1] row_mask:0xf bank_mask:0xf
	v_add_f32_dpp v91, v89, v89 quad_perm:[2,3,0,1] row_mask:0xf bank_mask:0xf
	v_cndmask_b32_e64 v88, v91, v90, s[4:5]
	v_cndmask_b32_e64 v93, v88, v92, s[6:7]
	v_cndmask_b32_e64 v94, v92, v88, s[6:7]
	s_waitcnt vmcnt(19)
	v_pk_mul_f32 v[252:253], v[236:237], v[76:77] op_sel_hi:[1,0]
	v_pk_mul_f32 v[254:255], v[244:245], v[76:77] op_sel_hi:[1,0]
	v_pk_fma_f32 v[252:253], v[238:239], v[76:77], v[252:253] op_sel:[0,1,0]
	v_pk_fma_f32 v[254:255], v[246:247], v[76:77], v[254:255] op_sel:[0,1,0]
	v_pk_fma_f32 v[252:253], v[240:241], v[78:79], v[252:253] op_sel_hi:[1,0,1]
	v_pk_fma_f32 v[254:255], v[248:249], v[78:79], v[254:255] op_sel_hi:[1,0,1]
	v_pk_fma_f32 v[252:253], v[242:243], v[78:79], v[252:253] op_sel:[0,1,0]
	v_pk_fma_f32 v[254:255], v[250:251], v[78:79], v[254:255] op_sel:[0,1,0]
	v_permlane16_swap_b32_e32 v124, v108
	v_add_f32_e32 v124, v124, v108
	v_add_f32_dpp v92, v94, v93 row_ror:4 row_mask:0xf bank_mask:0xf
	v_add_f32_dpp v80, v140, v140 quad_perm:[1,0,3,2] row_mask:0xf bank_mask:0xf
	v_add_f32_dpp v81, v141, v141 quad_perm:[1,0,3,2] row_mask:0xf bank_mask:0xf
	v_add_f32_dpp v82, v142, v142 quad_perm:[1,0,3,2] row_mask:0xf bank_mask:0xf
	v_add_f32_dpp v83, v143, v143 quad_perm:[1,0,3,2] row_mask:0xf bank_mask:0xf
	v_cndmask_b32_e32 v80, v82, v80, vcc
	v_cndmask_b32_e32 v81, v83, v81, vcc
	v_add_f32_dpp v86, v84, v84 quad_perm:[2,3,0,1] row_mask:0xf bank_mask:0xf
	v_add_f32_dpp v87, v85, v85 quad_perm:[2,3,0,1] row_mask:0xf bank_mask:0xf
	v_cndmask_b32_e64 v84, v87, v86, s[4:5]
	s_waitcnt vmcnt(18)
	v_pk_mul_f32 v[140:141], v[236:237], v[72:73] op_sel_hi:[1,0]
	v_pk_mul_f32 v[142:143], v[244:245], v[72:73] op_sel_hi:[1,0]
	v_pk_fma_f32 v[140:141], v[238:239], v[72:73], v[140:141] op_sel:[0,1,0]
	v_pk_fma_f32 v[142:143], v[246:247], v[72:73], v[142:143] op_sel:[0,1,0]
	v_pk_fma_f32 v[140:141], v[240:241], v[74:75], v[140:141] op_sel_hi:[1,0,1]
	v_pk_fma_f32 v[142:143], v[248:249], v[74:75], v[142:143] op_sel_hi:[1,0,1]
	v_pk_fma_f32 v[140:141], v[242:243], v[74:75], v[140:141] op_sel:[0,1,0]
	v_pk_fma_f32 v[142:143], v[250:251], v[74:75], v[142:143] op_sel:[0,1,0]
	v_add_f32_dpp v76, v252, v252 quad_perm:[1,0,3,2] row_mask:0xf bank_mask:0xf
	v_add_f32_dpp v77, v253, v253 quad_perm:[1,0,3,2] row_mask:0xf bank_mask:0xf
	v_add_f32_dpp v78, v254, v254 quad_perm:[1,0,3,2] row_mask:0xf bank_mask:0xf
	v_add_f32_dpp v79, v255, v255 quad_perm:[1,0,3,2] row_mask:0xf bank_mask:0xf
	v_cndmask_b32_e32 v76, v78, v76, vcc
	v_cndmask_b32_e32 v77, v79, v77, vcc
	v_add_f32_dpp v82, v80, v80 quad_perm:[2,3,0,1] row_mask:0xf bank_mask:0xf
	v_add_f32_dpp v83, v81, v81 quad_perm:[2,3,0,1] row_mask:0xf bank_mask:0xf
	v_cndmask_b32_e64 v80, v83, v82, s[4:5]
	v_cndmask_b32_e64 v85, v80, v84, s[6:7]
	v_cndmask_b32_e64 v86, v84, v80, s[6:7]
	s_waitcnt vmcnt(17)
	v_pk_mul_f32 v[252:253], v[236:237], v[68:69] op_sel_hi:[1,0]
	v_pk_mul_f32 v[254:255], v[244:245], v[68:69] op_sel_hi:[1,0]
	v_pk_fma_f32 v[252:253], v[238:239], v[68:69], v[252:253] op_sel:[0,1,0]
	v_pk_fma_f32 v[254:255], v[246:247], v[68:69], v[254:255] op_sel:[0,1,0]
	v_pk_fma_f32 v[252:253], v[240:241], v[70:71], v[252:253] op_sel_hi:[1,0,1]
	v_pk_fma_f32 v[254:255], v[248:249], v[70:71], v[254:255] op_sel_hi:[1,0,1]
	v_pk_fma_f32 v[252:253], v[242:243], v[70:71], v[252:253] op_sel:[0,1,0]
	v_pk_fma_f32 v[254:255], v[250:251], v[70:71], v[254:255] op_sel:[0,1,0]
	v_add_f32_dpp v84, v86, v85 row_ror:4 row_mask:0xf bank_mask:0xf
	v_cndmask_b32_e64 v93, v84, v92, s[64:65]
	v_cndmask_b32_e64 v94, v92, v84, s[64:65]
	v_add_f32_dpp v72, v140, v140 quad_perm:[1,0,3,2] row_mask:0xf bank_mask:0xf
	v_add_f32_dpp v73, v141, v141 quad_perm:[1,0,3,2] row_mask:0xf bank_mask:0xf
	v_add_f32_dpp v74, v142, v142 quad_perm:[1,0,3,2] row_mask:0xf bank_mask:0xf
	v_add_f32_dpp v75, v143, v143 quad_perm:[1,0,3,2] row_mask:0xf bank_mask:0xf
	v_cndmask_b32_e32 v72, v74, v72, vcc
	v_cndmask_b32_e32 v73, v75, v73, vcc
	v_add_f32_dpp v78, v76, v76 quad_perm:[2,3,0,1] row_mask:0xf bank_mask:0xf
	v_add_f32_dpp v79, v77, v77 quad_perm:[2,3,0,1] row_mask:0xf bank_mask:0xf
	v_cndmask_b32_e64 v76, v79, v78, s[4:5]
	s_waitcnt vmcnt(16)
	v_pk_mul_f32 v[140:141], v[236:237], v[64:65] op_sel_hi:[1,0]
	v_pk_mul_f32 v[142:143], v[244:245], v[64:65] op_sel_hi:[1,0]
	v_pk_fma_f32 v[140:141], v[238:239], v[64:65], v[140:141] op_sel:[0,1,0]
	v_pk_fma_f32 v[142:143], v[246:247], v[64:65], v[142:143] op_sel:[0,1,0]
	v_pk_fma_f32 v[140:141], v[240:241], v[66:67], v[140:141] op_sel_hi:[1,0,1]
	v_pk_fma_f32 v[142:143], v[248:249], v[66:67], v[142:143] op_sel_hi:[1,0,1]
	v_pk_fma_f32 v[140:141], v[242:243], v[66:67], v[140:141] op_sel:[0,1,0]
	v_pk_fma_f32 v[142:143], v[250:251], v[66:67], v[142:143] op_sel:[0,1,0]
	v_add_f32_dpp v92, v94, v93 row_ror:8 row_mask:0xf bank_mask:0xf
	v_add_f32_dpp v68, v252, v252 quad_perm:[1,0,3,2] row_mask:0xf bank_mask:0xf
	v_add_f32_dpp v69, v253, v253 quad_perm:[1,0,3,2] row_mask:0xf bank_mask:0xf
	v_add_f32_dpp v70, v254, v254 quad_perm:[1,0,3,2] row_mask:0xf bank_mask:0xf
	v_add_f32_dpp v71, v255, v255 quad_perm:[1,0,3,2] row_mask:0xf bank_mask:0xf
	v_cndmask_b32_e32 v68, v70, v68, vcc
	v_cndmask_b32_e32 v69, v71, v69, vcc
	v_add_f32_dpp v74, v72, v72 quad_perm:[2,3,0,1] row_mask:0xf bank_mask:0xf
	v_add_f32_dpp v75, v73, v73 quad_perm:[2,3,0,1] row_mask:0xf bank_mask:0xf
	v_cndmask_b32_e64 v72, v75, v74, s[4:5]
	v_cndmask_b32_e64 v77, v72, v76, s[6:7]
	v_cndmask_b32_e64 v78, v76, v72, s[6:7]
	s_waitcnt vmcnt(15)
	v_pk_mul_f32 v[252:253], v[236:237], v[60:61] op_sel_hi:[1,0]
	v_pk_mul_f32 v[254:255], v[244:245], v[60:61] op_sel_hi:[1,0]
	v_pk_fma_f32 v[252:253], v[238:239], v[60:61], v[252:253] op_sel:[0,1,0]
	v_pk_fma_f32 v[254:255], v[246:247], v[60:61], v[254:255] op_sel:[0,1,0]
	v_pk_fma_f32 v[252:253], v[240:241], v[62:63], v[252:253] op_sel_hi:[1,0,1]
	v_pk_fma_f32 v[254:255], v[248:249], v[62:63], v[254:255] op_sel_hi:[1,0,1]
	v_pk_fma_f32 v[252:253], v[242:243], v[62:63], v[252:253] op_sel:[0,1,0]
	v_pk_fma_f32 v[254:255], v[250:251], v[62:63], v[254:255] op_sel:[0,1,0]
	v_add_f32_dpp v76, v78, v77 row_ror:4 row_mask:0xf bank_mask:0xf
	v_add_f32_dpp v64, v140, v140 quad_perm:[1,0,3,2] row_mask:0xf bank_mask:0xf
	v_add_f32_dpp v65, v141, v141 quad_perm:[1,0,3,2] row_mask:0xf bank_mask:0xf
	v_add_f32_dpp v66, v142, v142 quad_perm:[1,0,3,2] row_mask:0xf bank_mask:0xf
	v_add_f32_dpp v67, v143, v143 quad_perm:[1,0,3,2] row_mask:0xf bank_mask:0xf
	v_cndmask_b32_e32 v64, v66, v64, vcc
	v_cndmask_b32_e32 v65, v67, v65, vcc
	v_add_f32_dpp v70, v68, v68 quad_perm:[2,3,0,1] row_mask:0xf bank_mask:0xf
	v_add_f32_dpp v71, v69, v69 quad_perm:[2,3,0,1] row_mask:0xf bank_mask:0xf
	v_cndmask_b32_e64 v68, v71, v70, s[4:5]
	s_waitcnt vmcnt(14)
	v_pk_mul_f32 v[140:141], v[236:237], v[56:57] op_sel_hi:[1,0]
	v_pk_mul_f32 v[142:143], v[244:245], v[56:57] op_sel_hi:[1,0]
	v_pk_fma_f32 v[140:141], v[238:239], v[56:57], v[140:141] op_sel:[0,1,0]
	v_pk_fma_f32 v[142:143], v[246:247], v[56:57], v[142:143] op_sel:[0,1,0]
	v_pk_fma_f32 v[140:141], v[240:241], v[58:59], v[140:141] op_sel_hi:[1,0,1]
	v_pk_fma_f32 v[142:143], v[248:249], v[58:59], v[142:143] op_sel_hi:[1,0,1]
	v_pk_fma_f32 v[140:141], v[242:243], v[58:59], v[140:141] op_sel:[0,1,0]
	v_pk_fma_f32 v[142:143], v[250:251], v[58:59], v[142:143] op_sel:[0,1,0]
	v_add_f32_dpp v60, v252, v252 quad_perm:[1,0,3,2] row_mask:0xf bank_mask:0xf
	v_add_f32_dpp v61, v253, v253 quad_perm:[1,0,3,2] row_mask:0xf bank_mask:0xf
	v_add_f32_dpp v62, v254, v254 quad_perm:[1,0,3,2] row_mask:0xf bank_mask:0xf
	v_add_f32_dpp v63, v255, v255 quad_perm:[1,0,3,2] row_mask:0xf bank_mask:0xf
	v_cndmask_b32_e32 v60, v62, v60, vcc
	v_cndmask_b32_e32 v61, v63, v61, vcc
	v_add_f32_dpp v66, v64, v64 quad_perm:[2,3,0,1] row_mask:0xf bank_mask:0xf
	v_add_f32_dpp v67, v65, v65 quad_perm:[2,3,0,1] row_mask:0xf bank_mask:0xf
	v_cndmask_b32_e64 v64, v67, v66, s[4:5]
	v_cndmask_b32_e64 v69, v64, v68, s[6:7]
	v_cndmask_b32_e64 v70, v68, v64, s[6:7]
	s_waitcnt vmcnt(13)
	v_pk_mul_f32 v[252:253], v[236:237], v[52:53] op_sel_hi:[1,0]
	v_pk_mul_f32 v[254:255], v[244:245], v[52:53] op_sel_hi:[1,0]
	v_pk_fma_f32 v[252:253], v[238:239], v[52:53], v[252:253] op_sel:[0,1,0]
	v_pk_fma_f32 v[254:255], v[246:247], v[52:53], v[254:255] op_sel:[0,1,0]
	v_pk_fma_f32 v[252:253], v[240:241], v[54:55], v[252:253] op_sel_hi:[1,0,1]
	v_pk_fma_f32 v[254:255], v[248:249], v[54:55], v[254:255] op_sel_hi:[1,0,1]
	v_pk_fma_f32 v[252:253], v[242:243], v[54:55], v[252:253] op_sel:[0,1,0]
	v_pk_fma_f32 v[254:255], v[250:251], v[54:55], v[254:255] op_sel:[0,1,0]
	v_add_f32_dpp v68, v70, v69 row_ror:4 row_mask:0xf bank_mask:0xf
	v_cndmask_b32_e64 v77, v68, v76, s[64:65]
	v_cndmask_b32_e64 v78, v76, v68, s[64:65]
	v_add_f32_dpp v56, v140, v140 quad_perm:[1,0,3,2] row_mask:0xf bank_mask:0xf
	v_add_f32_dpp v57, v141, v141 quad_perm:[1,0,3,2] row_mask:0xf bank_mask:0xf
	v_add_f32_dpp v58, v142, v142 quad_perm:[1,0,3,2] row_mask:0xf bank_mask:0xf
	v_add_f32_dpp v59, v143, v143 quad_perm:[1,0,3,2] row_mask:0xf bank_mask:0xf
	v_cndmask_b32_e32 v56, v58, v56, vcc
	v_cndmask_b32_e32 v57, v59, v57, vcc
	v_add_f32_dpp v62, v60, v60 quad_perm:[2,3,0,1] row_mask:0xf bank_mask:0xf
	v_add_f32_dpp v63, v61, v61 quad_perm:[2,3,0,1] row_mask:0xf bank_mask:0xf
	v_cndmask_b32_e64 v60, v63, v62, s[4:5]
	s_waitcnt vmcnt(12)
	v_pk_mul_f32 v[140:141], v[236:237], v[48:49] op_sel_hi:[1,0]
	v_pk_mul_f32 v[142:143], v[244:245], v[48:49] op_sel_hi:[1,0]
	v_pk_fma_f32 v[140:141], v[238:239], v[48:49], v[140:141] op_sel:[0,1,0]
	v_pk_fma_f32 v[142:143], v[246:247], v[48:49], v[142:143] op_sel:[0,1,0]
	v_pk_fma_f32 v[140:141], v[240:241], v[50:51], v[140:141] op_sel_hi:[1,0,1]
	v_pk_fma_f32 v[142:143], v[248:249], v[50:51], v[142:143] op_sel_hi:[1,0,1]
	v_pk_fma_f32 v[140:141], v[242:243], v[50:51], v[140:141] op_sel:[0,1,0]
	v_pk_fma_f32 v[142:143], v[250:251], v[50:51], v[142:143] op_sel:[0,1,0]
	v_add_f32_dpp v76, v78, v77 row_ror:8 row_mask:0xf bank_mask:0xf
	v_add_f32_dpp v52, v252, v252 quad_perm:[1,0,3,2] row_mask:0xf bank_mask:0xf
	v_add_f32_dpp v53, v253, v253 quad_perm:[1,0,3,2] row_mask:0xf bank_mask:0xf
	v_add_f32_dpp v54, v254, v254 quad_perm:[1,0,3,2] row_mask:0xf bank_mask:0xf
	v_add_f32_dpp v55, v255, v255 quad_perm:[1,0,3,2] row_mask:0xf bank_mask:0xf
	v_cndmask_b32_e32 v52, v54, v52, vcc
	v_cndmask_b32_e32 v53, v55, v53, vcc
	v_add_f32_dpp v58, v56, v56 quad_perm:[2,3,0,1] row_mask:0xf bank_mask:0xf
	v_add_f32_dpp v59, v57, v57 quad_perm:[2,3,0,1] row_mask:0xf bank_mask:0xf
	v_cndmask_b32_e64 v56, v59, v58, s[4:5]
	v_cndmask_b32_e64 v61, v56, v60, s[6:7]
	v_cndmask_b32_e64 v62, v60, v56, s[6:7]
	s_waitcnt vmcnt(11)
	v_pk_mul_f32 v[252:253], v[236:237], v[44:45] op_sel_hi:[1,0]
	v_pk_mul_f32 v[254:255], v[244:245], v[44:45] op_sel_hi:[1,0]
	v_pk_fma_f32 v[252:253], v[238:239], v[44:45], v[252:253] op_sel:[0,1,0]
	v_pk_fma_f32 v[254:255], v[246:247], v[44:45], v[254:255] op_sel:[0,1,0]
	v_pk_fma_f32 v[252:253], v[240:241], v[46:47], v[252:253] op_sel_hi:[1,0,1]
	v_pk_fma_f32 v[254:255], v[248:249], v[46:47], v[254:255] op_sel_hi:[1,0,1]
	v_pk_fma_f32 v[252:253], v[242:243], v[46:47], v[252:253] op_sel:[0,1,0]
	v_pk_fma_f32 v[254:255], v[250:251], v[46:47], v[254:255] op_sel:[0,1,0]
	v_permlane16_swap_b32_e32 v92, v76
	v_add_f32_e32 v92, v92, v76
	v_add_f32_dpp v60, v62, v61 row_ror:4 row_mask:0xf bank_mask:0xf
	v_add_f32_dpp v48, v140, v140 quad_perm:[1,0,3,2] row_mask:0xf bank_mask:0xf
	v_add_f32_dpp v49, v141, v141 quad_perm:[1,0,3,2] row_mask:0xf bank_mask:0xf
	v_add_f32_dpp v50, v142, v142 quad_perm:[1,0,3,2] row_mask:0xf bank_mask:0xf
	v_add_f32_dpp v51, v143, v143 quad_perm:[1,0,3,2] row_mask:0xf bank_mask:0xf
	v_cndmask_b32_e32 v48, v50, v48, vcc
	v_cndmask_b32_e32 v49, v51, v49, vcc
	v_add_f32_dpp v54, v52, v52 quad_perm:[2,3,0,1] row_mask:0xf bank_mask:0xf
	v_add_f32_dpp v55, v53, v53 quad_perm:[2,3,0,1] row_mask:0xf bank_mask:0xf
	v_cndmask_b32_e64 v52, v55, v54, s[4:5]
	s_waitcnt vmcnt(10)
; DI void attn_sample_item(const Params& p, int item, ldsp lds, int tid_) {
;     ...
;   SC_SCORE(kvA, 0)
;   SC_SCORE(kvB, 1)
	v_pk_mul_f32 v[140:141], v[236:237], v[40:41] op_sel_hi:[1,0]
	v_pk_mul_f32 v[142:143], v[244:245], v[40:41] op_sel_hi:[1,0]
	v_pk_fma_f32 v[140:141], v[238:239], v[40:41], v[140:141] op_sel:[0,1,0]
	v_pk_fma_f32 v[142:143], v[246:247], v[40:41], v[142:143] op_sel:[0,1,0]
	v_pk_fma_f32 v[140:141], v[240:241], v[42:43], v[140:141] op_sel_hi:[1,0,1]
	v_pk_fma_f32 v[142:143], v[248:249], v[42:43], v[142:143] op_sel_hi:[1,0,1]
	v_pk_fma_f32 v[140:141], v[242:243], v[42:43], v[140:141] op_sel:[0,1,0]
	v_pk_fma_f32 v[142:143], v[250:251], v[42:43], v[142:143] op_sel:[0,1,0]
	v_permlane32_swap_b32_e32 v124, v92
	v_add_f32_e32 v124, v124, v92
	ds_write_b32 v235, v124
	v_add_f32_dpp v44, v252, v252 quad_perm:[1,0,3,2] row_mask:0xf bank_mask:0xf
	v_add_f32_dpp v45, v253, v253 quad_perm:[1,0,3,2] row_mask:0xf bank_mask:0xf
	v_add_f32_dpp v46, v254, v254 quad_perm:[1,0,3,2] row_mask:0xf bank_mask:0xf
	v_add_f32_dpp v47, v255, v255 quad_perm:[1,0,3,2] row_mask:0xf bank_mask:0xf
	v_cndmask_b32_e32 v44, v46, v44, vcc
	v_cndmask_b32_e32 v45, v47, v45, vcc
	v_add_f32_dpp v50, v48, v48 quad_perm:[2,3,0,1] row_mask:0xf bank_mask:0xf
	v_add_f32_dpp v51, v49, v49 quad_perm:[2,3,0,1] row_mask:0xf bank_mask:0xf
	v_cndmask_b32_e64 v48, v51, v50, s[4:5]
	v_cndmask_b32_e64 v53, v48, v52, s[6:7]
	v_cndmask_b32_e64 v54, v52, v48, s[6:7]
	s_waitcnt vmcnt(9)
	v_pk_mul_f32 v[252:253], v[236:237], v[36:37] op_sel_hi:[1,0]
	v_pk_mul_f32 v[254:255], v[244:245], v[36:37] op_sel_hi:[1,0]
	v_pk_fma_f32 v[252:253], v[238:239], v[36:37], v[252:253] op_sel:[0,1,0]
	v_pk_fma_f32 v[254:255], v[246:247], v[36:37], v[254:255] op_sel:[0,1,0]
	v_pk_fma_f32 v[252:253], v[240:241], v[38:39], v[252:253] op_sel_hi:[1,0,1]
	v_pk_fma_f32 v[254:255], v[248:249], v[38:39], v[254:255] op_sel_hi:[1,0,1]
	v_pk_fma_f32 v[252:253], v[242:243], v[38:39], v[252:253] op_sel:[0,1,0]
	v_pk_fma_f32 v[254:255], v[250:251], v[38:39], v[254:255] op_sel:[0,1,0]
	v_add_f32_dpp v52, v54, v53 row_ror:4 row_mask:0xf bank_mask:0xf
	v_cndmask_b32_e64 v61, v52, v60, s[64:65]
	v_cndmask_b32_e64 v62, v60, v52, s[64:65]
	v_add_f32_dpp v40, v140, v140 quad_perm:[1,0,3,2] row_mask:0xf bank_mask:0xf
	v_add_f32_dpp v41, v141, v141 quad_perm:[1,0,3,2] row_mask:0xf bank_mask:0xf
	v_add_f32_dpp v42, v142, v142 quad_perm:[1,0,3,2] row_mask:0xf bank_mask:0xf
	v_add_f32_dpp v43, v143, v143 quad_perm:[1,0,3,2] row_mask:0xf bank_mask:0xf
	v_cndmask_b32_e32 v40, v42, v40, vcc
	v_cndmask_b32_e32 v41, v43, v41, vcc
	v_add_f32_dpp v46, v44, v44 quad_perm:[2,3,0,1] row_mask:0xf bank_mask:0xf
	v_add_f32_dpp v47, v45, v45 quad_perm:[2,3,0,1] row_mask:0xf bank_mask:0xf
	v_cndmask_b32_e64 v44, v47, v46, s[4:5]
	s_waitcnt vmcnt(8)
	v_pk_mul_f32 v[140:141], v[236:237], v[32:33] op_sel_hi:[1,0]
	v_pk_mul_f32 v[142:143], v[244:245], v[32:33] op_sel_hi:[1,0]
	v_pk_fma_f32 v[140:141], v[238:239], v[32:33], v[140:141] op_sel:[0,1,0]
	v_pk_fma_f32 v[142:143], v[246:247], v[32:33], v[142:143] op_sel:[0,1,0]
	v_pk_fma_f32 v[140:141], v[240:241], v[34:35], v[140:141] op_sel_hi:[1,0,1]
	v_pk_fma_f32 v[142:143], v[248:249], v[34:35], v[142:143] op_sel_hi:[1,0,1]
	v_pk_fma_f32 v[140:141], v[242:243], v[34:35], v[140:141] op_sel:[0,1,0]
	v_pk_fma_f32 v[142:143], v[250:251], v[34:35], v[142:143] op_sel:[0,1,0]
	v_add_f32_dpp v60, v62, v61 row_ror:8 row_mask:0xf bank_mask:0xf
	v_add_f32_dpp v36, v252, v252 quad_perm:[1,0,3,2] row_mask:0xf bank_mask:0xf
	v_add_f32_dpp v37, v253, v253 quad_perm:[1,0,3,2] row_mask:0xf bank_mask:0xf
	v_add_f32_dpp v38, v254, v254 quad_perm:[1,0,3,2] row_mask:0xf bank_mask:0xf
	v_add_f32_dpp v39, v255, v255 quad_perm:[1,0,3,2] row_mask:0xf bank_mask:0xf
	v_cndmask_b32_e32 v36, v38, v36, vcc
	v_cndmask_b32_e32 v37, v39, v37, vcc
	v_add_f32_dpp v42, v40, v40 quad_perm:[2,3,0,1] row_mask:0xf bank_mask:0xf
	v_add_f32_dpp v43, v41, v41 quad_perm:[2,3,0,1] row_mask:0xf bank_mask:0xf
	v_cndmask_b32_e64 v40, v43, v42, s[4:5]
	v_cndmask_b32_e64 v45, v40, v44, s[6:7]
	v_cndmask_b32_e64 v46, v44, v40, s[6:7]
	s_waitcnt vmcnt(7)
	v_pk_mul_f32 v[252:253], v[236:237], v[28:29] op_sel_hi:[1,0]
	v_pk_mul_f32 v[254:255], v[244:245], v[28:29] op_sel_hi:[1,0]
	v_pk_fma_f32 v[252:253], v[238:239], v[28:29], v[252:253] op_sel:[0,1,0]
	v_pk_fma_f32 v[254:255], v[246:247], v[28:29], v[254:255] op_sel:[0,1,0]
	v_pk_fma_f32 v[252:253], v[240:241], v[30:31], v[252:253] op_sel_hi:[1,0,1]
	v_pk_fma_f32 v[254:255], v[248:249], v[30:31], v[254:255] op_sel_hi:[1,0,1]
	v_pk_fma_f32 v[252:253], v[242:243], v[30:31], v[252:253] op_sel:[0,1,0]
	v_pk_fma_f32 v[254:255], v[250:251], v[30:31], v[254:255] op_sel:[0,1,0]
	v_add_f32_dpp v44, v46, v45 row_ror:4 row_mask:0xf bank_mask:0xf
	v_add_f32_dpp v32, v140, v140 quad_perm:[1,0,3,2] row_mask:0xf bank_mask:0xf
	v_add_f32_dpp v33, v141, v141 quad_perm:[1,0,3,2] row_mask:0xf bank_mask:0xf
	v_add_f32_dpp v34, v142, v142 quad_perm:[1,0,3,2] row_mask:0xf bank_mask:0xf
	v_add_f32_dpp v35, v143, v143 quad_perm:[1,0,3,2] row_mask:0xf bank_mask:0xf
	v_cndmask_b32_e32 v32, v34, v32, vcc
	v_cndmask_b32_e32 v33, v35, v33, vcc
	v_add_f32_dpp v38, v36, v36 quad_perm:[2,3,0,1] row_mask:0xf bank_mask:0xf
	v_add_f32_dpp v39, v37, v37 quad_perm:[2,3,0,1] row_mask:0xf bank_mask:0xf
	v_cndmask_b32_e64 v36, v39, v38, s[4:5]
	s_waitcnt vmcnt(6)
	v_pk_mul_f32 v[140:141], v[236:237], v[24:25] op_sel_hi:[1,0]
	v_pk_mul_f32 v[142:143], v[244:245], v[24:25] op_sel_hi:[1,0]
	v_pk_fma_f32 v[140:141], v[238:239], v[24:25], v[140:141] op_sel:[0,1,0]
	v_pk_fma_f32 v[142:143], v[246:247], v[24:25], v[142:143] op_sel:[0,1,0]
	v_pk_fma_f32 v[140:141], v[240:241], v[26:27], v[140:141] op_sel_hi:[1,0,1]
	v_pk_fma_f32 v[142:143], v[248:249], v[26:27], v[142:143] op_sel_hi:[1,0,1]
	v_pk_fma_f32 v[140:141], v[242:243], v[26:27], v[140:141] op_sel:[0,1,0]
	v_pk_fma_f32 v[142:143], v[250:251], v[26:27], v[142:143] op_sel:[0,1,0]
	v_add_f32_dpp v28, v252, v252 quad_perm:[1,0,3,2] row_mask:0xf bank_mask:0xf
	v_add_f32_dpp v29, v253, v253 quad_perm:[1,0,3,2] row_mask:0xf bank_mask:0xf
	v_add_f32_dpp v30, v254, v254 quad_perm:[1,0,3,2] row_mask:0xf bank_mask:0xf
	v_add_f32_dpp v31, v255, v255 quad_perm:[1,0,3,2] row_mask:0xf bank_mask:0xf
	v_cndmask_b32_e32 v28, v30, v28, vcc
	v_cndmask_b32_e32 v29, v31, v29, vcc
	v_add_f32_dpp v34, v32, v32 quad_perm:[2,3,0,1] row_mask:0xf bank_mask:0xf
	v_add_f32_dpp v35, v33, v33 quad_perm:[2,3,0,1] row_mask:0xf bank_mask:0xf
	v_cndmask_b32_e64 v32, v35, v34, s[4:5]
	v_cndmask_b32_e64 v37, v32, v36, s[6:7]
	v_cndmask_b32_e64 v38, v36, v32, s[6:7]
	s_waitcnt vmcnt(5)
	v_pk_mul_f32 v[252:253], v[236:237], v[20:21] op_sel_hi:[1,0]
	v_pk_mul_f32 v[254:255], v[244:245], v[20:21] op_sel_hi:[1,0]
	v_pk_fma_f32 v[252:253], v[238:239], v[20:21], v[252:253] op_sel:[0,1,0]
	v_pk_fma_f32 v[254:255], v[246:247], v[20:21], v[254:255] op_sel:[0,1,0]
	v_pk_fma_f32 v[252:253], v[240:241], v[22:23], v[252:253] op_sel_hi:[1,0,1]
	v_pk_fma_f32 v[254:255], v[248:249], v[22:23], v[254:255] op_sel_hi:[1,0,1]
	v_pk_fma_f32 v[252:253], v[242:243], v[22:23], v[252:253] op_sel:[0,1,0]
	v_pk_fma_f32 v[254:255], v[250:251], v[22:23], v[254:255] op_sel:[0,1,0]
	v_add_f32_dpp v36, v38, v37 row_ror:4 row_mask:0xf bank_mask:0xf
	v_cndmask_b32_e64 v45, v36, v44, s[64:65]
	v_cndmask_b32_e64 v46, v44, v36, s[64:65]
	v_add_f32_dpp v24, v140, v140 quad_perm:[1,0,3,2] row_mask:0xf bank_mask:0xf
	v_add_f32_dpp v25, v141, v141 quad_perm:[1,0,3,2] row_mask:0xf bank_mask:0xf
	v_add_f32_dpp v26, v142, v142 quad_perm:[1,0,3,2] row_mask:0xf bank_mask:0xf
	v_add_f32_dpp v27, v143, v143 quad_perm:[1,0,3,2] row_mask:0xf bank_mask:0xf
	v_cndmask_b32_e32 v24, v26, v24, vcc
	v_cndmask_b32_e32 v25, v27, v25, vcc
	v_add_f32_dpp v30, v28, v28 quad_perm:[2,3,0,1] row_mask:0xf bank_mask:0xf
	v_add_f32_dpp v31, v29, v29 quad_perm:[2,3,0,1] row_mask:0xf bank_mask:0xf
	v_cndmask_b32_e64 v28, v31, v30, s[4:5]
	s_waitcnt vmcnt(4)
	v_pk_mul_f32 v[140:141], v[236:237], v[16:17] op_sel_hi:[1,0]
	v_pk_mul_f32 v[142:143], v[244:245], v[16:17] op_sel_hi:[1,0]
	v_pk_fma_f32 v[140:141], v[238:239], v[16:17], v[140:141] op_sel:[0,1,0]
	v_pk_fma_f32 v[142:143], v[246:247], v[16:17], v[142:143] op_sel:[0,1,0]
	v_pk_fma_f32 v[140:141], v[240:241], v[18:19], v[140:141] op_sel_hi:[1,0,1]
	v_pk_fma_f32 v[142:143], v[248:249], v[18:19], v[142:143] op_sel_hi:[1,0,1]
	v_pk_fma_f32 v[140:141], v[242:243], v[18:19], v[140:141] op_sel:[0,1,0]
	v_pk_fma_f32 v[142:143], v[250:251], v[18:19], v[142:143] op_sel:[0,1,0]
	v_add_f32_dpp v44, v46, v45 row_ror:8 row_mask:0xf bank_mask:0xf
	v_add_f32_dpp v20, v252, v252 quad_perm:[1,0,3,2] row_mask:0xf bank_mask:0xf
	v_add_f32_dpp v21, v253, v253 quad_perm:[1,0,3,2] row_mask:0xf bank_mask:0xf
	v_add_f32_dpp v22, v254, v254 quad_perm:[1,0,3,2] row_mask:0xf bank_mask:0xf
	v_add_f32_dpp v23, v255, v255 quad_perm:[1,0,3,2] row_mask:0xf bank_mask:0xf
	v_cndmask_b32_e32 v20, v22, v20, vcc
	v_cndmask_b32_e32 v21, v23, v21, vcc
	v_add_f32_dpp v26, v24, v24 quad_perm:[2,3,0,1] row_mask:0xf bank_mask:0xf
	v_add_f32_dpp v27, v25, v25 quad_perm:[2,3,0,1] row_mask:0xf bank_mask:0xf
	v_cndmask_b32_e64 v24, v27, v26, s[4:5]
	v_cndmask_b32_e64 v29, v24, v28, s[6:7]
	v_cndmask_b32_e64 v30, v28, v24, s[6:7]
	s_waitcnt vmcnt(3)
	v_pk_mul_f32 v[252:253], v[236:237], v[12:13] op_sel_hi:[1,0]
	v_pk_mul_f32 v[254:255], v[244:245], v[12:13] op_sel_hi:[1,0]
	v_pk_fma_f32 v[252:253], v[238:239], v[12:13], v[252:253] op_sel:[0,1,0]
	v_pk_fma_f32 v[254:255], v[246:247], v[12:13], v[254:255] op_sel:[0,1,0]
	v_pk_fma_f32 v[252:253], v[240:241], v[14:15], v[252:253] op_sel_hi:[1,0,1]
	v_pk_fma_f32 v[254:255], v[248:249], v[14:15], v[254:255] op_sel_hi:[1,0,1]
	v_pk_fma_f32 v[252:253], v[242:243], v[14:15], v[252:253] op_sel:[0,1,0]
	v_pk_fma_f32 v[254:255], v[250:251], v[14:15], v[254:255] op_sel:[0,1,0]
	v_permlane16_swap_b32_e32 v60, v44
	v_add_f32_e32 v60, v60, v44
	v_add_f32_dpp v28, v30, v29 row_ror:4 row_mask:0xf bank_mask:0xf
	v_add_f32_dpp v16, v140, v140 quad_perm:[1,0,3,2] row_mask:0xf bank_mask:0xf
	v_add_f32_dpp v17, v141, v141 quad_perm:[1,0,3,2] row_mask:0xf bank_mask:0xf
	v_add_f32_dpp v18, v142, v142 quad_perm:[1,0,3,2] row_mask:0xf bank_mask:0xf
	v_add_f32_dpp v19, v143, v143 quad_perm:[1,0,3,2] row_mask:0xf bank_mask:0xf
	v_cndmask_b32_e32 v16, v18, v16, vcc
	v_cndmask_b32_e32 v17, v19, v17, vcc
	v_add_f32_dpp v22, v20, v20 quad_perm:[2,3,0,1] row_mask:0xf bank_mask:0xf
	v_add_f32_dpp v23, v21, v21 quad_perm:[2,3,0,1] row_mask:0xf bank_mask:0xf
	v_cndmask_b32_e64 v20, v23, v22, s[4:5]
	s_waitcnt vmcnt(2)
	v_pk_mul_f32 v[140:141], v[236:237], v[8:9] op_sel_hi:[1,0]
	v_pk_mul_f32 v[142:143], v[244:245], v[8:9] op_sel_hi:[1,0]
	v_pk_fma_f32 v[140:141], v[238:239], v[8:9], v[140:141] op_sel:[0,1,0]
	v_pk_fma_f32 v[142:143], v[246:247], v[8:9], v[142:143] op_sel:[0,1,0]
	v_pk_fma_f32 v[140:141], v[240:241], v[10:11], v[140:141] op_sel_hi:[1,0,1]
	v_pk_fma_f32 v[142:143], v[248:249], v[10:11], v[142:143] op_sel_hi:[1,0,1]
	v_pk_fma_f32 v[140:141], v[242:243], v[10:11], v[140:141] op_sel:[0,1,0]
	v_pk_fma_f32 v[142:143], v[250:251], v[10:11], v[142:143] op_sel:[0,1,0]
	v_add_f32_dpp v12, v252, v252 quad_perm:[1,0,3,2] row_mask:0xf bank_mask:0xf
	v_add_f32_dpp v13, v253, v253 quad_perm:[1,0,3,2] row_mask:0xf bank_mask:0xf
	v_add_f32_dpp v14, v254, v254 quad_perm:[1,0,3,2] row_mask:0xf bank_mask:0xf
	v_add_f32_dpp v15, v255, v255 quad_perm:[1,0,3,2] row_mask:0xf bank_mask:0xf
	v_cndmask_b32_e32 v12, v14, v12, vcc
	v_cndmask_b32_e32 v13, v15, v13, vcc
	v_add_f32_dpp v18, v16, v16 quad_perm:[2,3,0,1] row_mask:0xf bank_mask:0xf
	v_add_f32_dpp v19, v17, v17 quad_perm:[2,3,0,1] row_mask:0xf bank_mask:0xf
	v_cndmask_b32_e64 v16, v19, v18, s[4:5]
	v_cndmask_b32_e64 v21, v16, v20, s[6:7]
	v_cndmask_b32_e64 v22, v20, v16, s[6:7]
	s_waitcnt vmcnt(1)
	v_pk_mul_f32 v[252:253], v[236:237], v[4:5] op_sel_hi:[1,0]
	v_pk_mul_f32 v[254:255], v[244:245], v[4:5] op_sel_hi:[1,0]
	v_pk_fma_f32 v[252:253], v[238:239], v[4:5], v[252:253] op_sel:[0,1,0]
	v_pk_fma_f32 v[254:255], v[246:247], v[4:5], v[254:255] op_sel:[0,1,0]
	v_pk_fma_f32 v[252:253], v[240:241], v[6:7], v[252:253] op_sel_hi:[1,0,1]
	v_pk_fma_f32 v[254:255], v[248:249], v[6:7], v[254:255] op_sel_hi:[1,0,1]
	v_pk_fma_f32 v[252:253], v[242:243], v[6:7], v[252:253] op_sel:[0,1,0]
	v_pk_fma_f32 v[254:255], v[250:251], v[6:7], v[254:255] op_sel:[0,1,0]
	v_add_f32_dpp v20, v22, v21 row_ror:4 row_mask:0xf bank_mask:0xf
	v_cndmask_b32_e64 v29, v20, v28, s[64:65]
	v_cndmask_b32_e64 v30, v28, v20, s[64:65]
	v_add_f32_dpp v8, v140, v140 quad_perm:[1,0,3,2] row_mask:0xf bank_mask:0xf
	v_add_f32_dpp v9, v141, v141 quad_perm:[1,0,3,2] row_mask:0xf bank_mask:0xf
	v_add_f32_dpp v10, v142, v142 quad_perm:[1,0,3,2] row_mask:0xf bank_mask:0xf
	v_add_f32_dpp v11, v143, v143 quad_perm:[1,0,3,2] row_mask:0xf bank_mask:0xf
	v_cndmask_b32_e32 v8, v10, v8, vcc
	v_cndmask_b32_e32 v9, v11, v9, vcc
	v_add_f32_dpp v14, v12, v12 quad_perm:[2,3,0,1] row_mask:0xf bank_mask:0xf
	v_add_f32_dpp v15, v13, v13 quad_perm:[2,3,0,1] row_mask:0xf bank_mask:0xf
	v_cndmask_b32_e64 v12, v15, v14, s[4:5]
	s_waitcnt vmcnt(0)
; DI void lbar() { asm volatile("s_waitcnt lgkmcnt(0)" ::: "memory"); __builtin_amdgcn_s_barrier(); asm volatile("" ::: "memory"); }
; DI void attn_sample_item(const Params& p, int item, ldsp lds, int tid_) {
;     ...
;   SC_SCORE(kvA, 0)
;   SC_SCORE(kvB, 1)
;     ...
;   f32x4 vvA[16], vvB[16];
; #pragma unroll
;   for (int j = 0; j < 16; ++j) vvA[j] = __builtin_nontemporal_load((const f32x4*)(cv + (size_t)(wid * 32 + j) * 1024 + lane * 4));
;   lbar();
	v_pk_mul_f32 v[140:141], v[236:237], v[0:1] op_sel_hi:[1,0]
	v_pk_mul_f32 v[142:143], v[244:245], v[0:1] op_sel_hi:[1,0]
	v_pk_fma_f32 v[140:141], v[238:239], v[0:1], v[140:141] op_sel:[0,1,0]
	v_pk_fma_f32 v[142:143], v[246:247], v[0:1], v[142:143] op_sel:[0,1,0]
	v_pk_fma_f32 v[140:141], v[240:241], v[2:3], v[140:141] op_sel_hi:[1,0,1]
	v_pk_fma_f32 v[142:143], v[248:249], v[2:3], v[142:143] op_sel_hi:[1,0,1]
	v_pk_fma_f32 v[140:141], v[242:243], v[2:3], v[140:141] op_sel:[0,1,0]
	v_pk_fma_f32 v[142:143], v[250:251], v[2:3], v[142:143] op_sel:[0,1,0]
	v_add_f32_dpp v28, v30, v29 row_ror:8 row_mask:0xf bank_mask:0xf
	v_add_f32_dpp v4, v252, v252 quad_perm:[1,0,3,2] row_mask:0xf bank_mask:0xf
	v_add_f32_dpp v5, v253, v253 quad_perm:[1,0,3,2] row_mask:0xf bank_mask:0xf
	v_add_f32_dpp v6, v254, v254 quad_perm:[1,0,3,2] row_mask:0xf bank_mask:0xf
	v_add_f32_dpp v7, v255, v255 quad_perm:[1,0,3,2] row_mask:0xf bank_mask:0xf
	v_cndmask_b32_e32 v4, v6, v4, vcc
	v_cndmask_b32_e32 v5, v7, v5, vcc
	v_add_f32_dpp v10, v8, v8 quad_perm:[2,3,0,1] row_mask:0xf bank_mask:0xf
	v_add_f32_dpp v11, v9, v9 quad_perm:[2,3,0,1] row_mask:0xf bank_mask:0xf
	v_cndmask_b32_e64 v8, v11, v10, s[4:5]
	v_cndmask_b32_e64 v13, v8, v12, s[6:7]
	v_cndmask_b32_e64 v14, v12, v8, s[6:7]
	s_nop 1
	v_add_f32_dpp v12, v14, v13 row_ror:4 row_mask:0xf bank_mask:0xf
	v_add_f32_dpp v0, v140, v140 quad_perm:[1,0,3,2] row_mask:0xf bank_mask:0xf
	v_add_f32_dpp v1, v141, v141 quad_perm:[1,0,3,2] row_mask:0xf bank_mask:0xf
	v_add_f32_dpp v2, v142, v142 quad_perm:[1,0,3,2] row_mask:0xf bank_mask:0xf
	v_add_f32_dpp v3, v143, v143 quad_perm:[1,0,3,2] row_mask:0xf bank_mask:0xf
	v_cndmask_b32_e32 v0, v2, v0, vcc
	v_cndmask_b32_e32 v1, v3, v1, vcc
	v_add_f32_dpp v6, v4, v4 quad_perm:[2,3,0,1] row_mask:0xf bank_mask:0xf
	v_add_f32_dpp v7, v5, v5 quad_perm:[2,3,0,1] row_mask:0xf bank_mask:0xf
	v_cndmask_b32_e64 v4, v7, v6, s[4:5]
	v_add_f32_dpp v2, v0, v0 quad_perm:[2,3,0,1] row_mask:0xf bank_mask:0xf
	v_add_f32_dpp v3, v1, v1 quad_perm:[2,3,0,1] row_mask:0xf bank_mask:0xf
	v_cndmask_b32_e64 v0, v3, v2, s[4:5]
	v_cndmask_b32_e64 v5, v0, v4, s[6:7]
	v_cndmask_b32_e64 v6, v4, v0, s[6:7]
	s_nop 1
	v_add_f32_dpp v4, v6, v5 row_ror:4 row_mask:0xf bank_mask:0xf
	v_cndmask_b32_e64 v13, v4, v12, s[64:65]
	v_cndmask_b32_e64 v14, v12, v4, s[64:65]
	s_nop 1
	v_add_f32_dpp v12, v14, v13 row_ror:8 row_mask:0xf bank_mask:0xf
	s_nop 1
	v_permlane16_swap_b32_e32 v28, v12
	v_add_f32_e32 v28, v28, v12
	s_nop 1
	v_permlane32_swap_b32_e32 v60, v28
	v_add_f32_e32 v60, v60, v28
	ds_write_b32 v235, v60 offset:64
	v_add_u32_e32 v100, v158, v144
	global_load_dwordx4 v[100:103], v100, s[66:67] nt
	v_add_u32_e32 v92, v162, v144
	global_load_dwordx4 v[92:95], v92, s[66:67] nt
	v_add_u32_e32 v112, v164, v144
	global_load_dwordx4 v[112:115], v112, s[66:67] nt
	v_add_u32_e32 v108, v168, v144
	global_load_dwordx4 v[108:111], v108, s[66:67] nt
	v_add_u32_e32 v120, v172, v144
	global_load_dwordx4 v[120:123], v120, s[66:67] nt
	v_add_u32_e32 v116, v176, v144
	global_load_dwordx4 v[116:119], v116, s[66:67] nt
	v_add_u32_e32 v124, v180, v144
	global_load_dwordx4 v[124:127], v124, s[66:67] nt
	v_add_u32_e32 v104, v184, v144
	global_load_dwordx4 v[104:107], v104, s[66:67] nt
	v_add_u32_e32 v68, v188, v144
	global_load_dwordx4 v[68:71], v68, s[66:67] nt
	v_add_u32_e32 v64, v192, v144
	global_load_dwordx4 v[64:67], v64, s[66:67] nt
	v_add_u32_e32 v80, v196, v144
	global_load_dwordx4 v[80:83], v80, s[66:67] nt
	v_add_u32_e32 v76, v200, v144
	global_load_dwordx4 v[76:79], v76, s[66:67] nt
	v_add_u32_e32 v88, v202, v144
	global_load_dwordx4 v[88:91], v88, s[66:67] nt
	v_add_u32_e32 v84, v204, v144
	global_load_dwordx4 v[84:87], v84, s[66:67] nt
	v_add_u32_e32 v96, v206, v144
	global_load_dwordx4 v[96:99], v96, s[66:67] nt
	v_add_u32_e32 v72, v208, v144
	global_load_dwordx4 v[72:75], v72, s[66:67] nt
	v_add_u32_e32 v40, v146, v144
	global_load_dwordx4 v[40:43], v40, s[66:67] nt
	v_add_u32_e32 v36, v148, v144
	global_load_dwordx4 v[36:39], v36, s[66:67] nt
	v_add_u32_e32 v48, v150, v144
	global_load_dwordx4 v[48:51], v48, s[66:67] nt
	v_add_u32_e32 v44, v152, v144
	global_load_dwordx4 v[44:47], v44, s[66:67] nt
	v_add_u32_e32 v56, v154, v144
	global_load_dwordx4 v[56:59], v56, s[66:67] nt
	v_add_u32_e32 v52, v156, v144
	global_load_dwordx4 v[52:55], v52, s[66:67] nt
	v_add_u32_e32 v60, v160, v144
	global_load_dwordx4 v[60:63], v60, s[66:67] nt
	v_add_u32_e32 v32, v166, v144
	global_load_dwordx4 v[32:35], v32, s[66:67] nt
	v_add_u32_e32 v12, v170, v144
	global_load_dwordx4 v[12:15], v12, s[66:67] nt
	v_add_u32_e32 v4, v174, v144
	global_load_dwordx4 v[4:7], v4, s[66:67] nt
	v_add_u32_e32 v20, v178, v144
	global_load_dwordx4 v[20:23], v20, s[66:67] nt
	v_add_u32_e32 v8, v182, v144
	global_load_dwordx4 v[8:11], v8, s[66:67] nt
	v_add_u32_e32 v24, v186, v144
	global_load_dwordx4 v[24:27], v24, s[66:67] nt
	v_add_u32_e32 v16, v190, v144
	global_load_dwordx4 v[16:19], v16, s[66:67] nt
	v_add_u32_e32 v28, v194, v144
	global_load_dwordx4 v[28:31], v28, s[66:67] nt
	v_add_u32_e32 v0, v198, v144
	global_load_dwordx4 v[0:3], v0, s[66:67] nt
	v_lshlrev_b32_e32 v240, 2, v223
	s_waitcnt lgkmcnt(0)
	s_barrier
	v_cmp_gt_i32_e32 vcc, 4, v210
	s_and_saveexec_b64 s[4:5], vcc
	s_cbranch_execz .LBB0_1675

; DI float wave_sum(float v) { for (int o = 32; o >= 1; o >>= 1) v += __shfl_xor(v, o); return v; }
; DI void attn_sample_item(const Params& p, int item, ldsp lds, int tid_) {
;     ...
;   if (wid < 4) {
;     float v[4]; float mx = -1e30f;
; #pragma unroll
;     for (int j = 0; j < 4; ++j) { v[j] = SC[wid * 256 + j * 64 + lane]; mx = fmaxf(mx, v[j]); }
;     for (int o = 32; o >= 1; o >>= 1) mx = fmaxf(mx, __shfl_xor(mx, o));
;     float s = 0.f;
; #pragma unroll
;     for (int j = 0; j < 4; ++j) { v[j] = __expf(v[j] - mx); s += v[j]; }
;     s = wave_sum(s); const float inv = 1.f / s;
; #pragma unroll
;     for (int j = 0; j < 4; ++j) SC[wid * 256 + j * 64 + lane] = v[j] * inv;
;   }
	v_lshlrev_b32_e32 v241, 10, v210
	v_add3_u32 v244, 16, v241, v240
	ds_read2st64_b32 v[240:241], v244 offset1:1
	ds_read2st64_b32 v[242:243], v244 offset0:2 offset1:3
	s_waitcnt lgkmcnt(1)
	v_max3_f32 v245, v240, s35, v241
	s_waitcnt lgkmcnt(0)
	v_max3_f32 v245, v245, v242, v243
	ds_bpermute_b32 v246, v133, v245
	s_waitcnt lgkmcnt(0)
	v_max_f32_e32 v246, v246, v246
	v_max_f32_e32 v245, v245, v246
	ds_bpermute_b32 v246, v132, v245
	s_waitcnt lgkmcnt(0)
	v_max_f32_e32 v246, v246, v246
	v_max_f32_e32 v245, v245, v246
	ds_bpermute_b32 v246, v131, v245
	s_waitcnt lgkmcnt(0)
	v_max_f32_e32 v246, v246, v246
	v_max_f32_e32 v245, v245, v246
	ds_bpermute_b32 v246, v130, v245
	s_waitcnt lgkmcnt(0)
	v_max_f32_e32 v246, v246, v246
	v_max_f32_e32 v245, v245, v246
	ds_bpermute_b32 v246, v129, v245
	s_waitcnt lgkmcnt(0)
	v_max_f32_e32 v246, v246, v246
	v_max_f32_e32 v245, v245, v246
	ds_bpermute_b32 v246, v128, v245
	s_waitcnt lgkmcnt(0)
	v_max_f32_e32 v246, v246, v246
	v_max_f32_e32 v245, v245, v246
	v_sub_f32_e32 v240, v240, v245
	v_sub_f32_e32 v241, v241, v245
	v_mul_f32_e32 v240, 0x3fb8aa3b, v240
	v_sub_f32_e32 v242, v242, v245
	v_mul_f32_e32 v241, 0x3fb8aa3b, v241
	v_exp_f32_e32 v240, v240
	v_sub_f32_e32 v243, v243, v245
	v_mul_f32_e32 v242, 0x3fb8aa3b, v242
	v_exp_f32_e32 v241, v241
	v_mul_f32_e32 v243, 0x3fb8aa3b, v243
	v_exp_f32_e32 v242, v242
	v_exp_f32_e32 v243, v243
	v_add_f32_e32 v245, 0, v240
	v_add_f32_e32 v245, v241, v245
	v_add_f32_e32 v245, v242, v245
	v_add_f32_e32 v245, v243, v245
	ds_bpermute_b32 v246, v133, v245
	s_waitcnt lgkmcnt(0)
	v_add_f32_e32 v245, v245, v246
	ds_bpermute_b32 v246, v132, v245
	s_waitcnt lgkmcnt(0)
	v_add_f32_e32 v245, v245, v246
	ds_bpermute_b32 v246, v131, v245
	s_waitcnt lgkmcnt(0)
	v_add_f32_e32 v245, v245, v246
	ds_bpermute_b32 v246, v130, v245
	s_waitcnt lgkmcnt(0)
	v_add_f32_e32 v245, v245, v246
	ds_bpermute_b32 v246, v129, v245
	s_waitcnt lgkmcnt(0)
	v_add_f32_e32 v245, v245, v246
	ds_bpermute_b32 v246, v128, v245
	s_waitcnt lgkmcnt(0)
	v_add_f32_e32 v245, v245, v246
	v_div_scale_f32 v246, s[6:7], v245, v245, 1.0
	v_rcp_f32_e32 v247, v246
	v_div_scale_f32 v248, vcc, 1.0, v245, 1.0
	v_fma_f32 v249, -v246, v247, 1.0
	v_fmac_f32_e32 v247, v249, v247
	v_mul_f32_e32 v249, v248, v247
	v_fma_f32 v250, -v246, v249, v248
	v_fmac_f32_e32 v249, v250, v247
	v_fma_f32 v246, -v246, v249, v248
	v_div_fmas_f32 v246, v246, v247, v249
	v_div_fixup_f32 v245, v246, v245, 1.0
	v_mul_f32_e32 v240, v240, v245
	v_mul_f32_e32 v241, v241, v245
	v_mul_f32_e32 v242, v242, v245
	v_mul_f32_e32 v243, v243, v245
	ds_write2st64_b32 v244, v240, v241 offset1:1
	ds_write2st64_b32 v244, v242, v243 offset0:2 offset1:3
	s_branch .LBB0_1675
